# v87 + kinv: loop-invariant second-K-tile LDS read bases kept in v254/v255 (set once per unit) instead of 2 v_add per K-loop body (P1/S3/S4)
# speedup vs baseline: 1.0071x; 1.0034x over previous
.LBB0_367:
	s_ashr_i32 s55, s54, 31
	s_lshl_b64 s[2:3], s[54:55], 19
	s_add_u32 s58, s4, s2
	s_addc_u32 s59, s5, s3
	s_and_b64 s[2:3], s[56:57], exec
	s_cselect_b32 s2, s59, s7
	s_cselect_b32 s3, s58, s6
	s_ashr_i32 s53, s52, 31
	s_lshl_b64 s[10:11], s[52:53], 19
	s_add_u32 s60, s15, s10
	s_addc_u32 s61, s78, s11
	s_and_b64 s[10:11], s[56:57], exec
	s_cselect_b32 s12, s61, s9
	s_cselect_b32 s13, s60, s8
	s_add_u32 s6, s6, 0x40080
	s_addc_u32 s7, s7, 0
	s_add_u32 s24, s8, 0x100
	s_addc_u32 s25, s9, 0
	s_mov_b32 s26, -2
	v_add_u32_e32 v254, 0x18000, v173
	v_add_u32_e32 v255, 0x1c000, v173
	ds_read_b128 v[114:117], v197
	ds_read_b128 v[134:137], v197 offset:1024
	ds_read_b128 v[138:141], v197 offset:2048
	ds_read_b128 v[142:145], v197 offset:3072
	ds_read_b128 v[146:149], v198
	ds_read_b128 v[150:153], v198 offset:1024
	ds_read_b128 v[154:157], v198 offset:2048
	ds_read_b128 v[158:161], v198 offset:3072
	s_add_u32 s0, s6, 0xfffc0080
	s_addc_u32 s8, s7, -1
	s_cmp_eq_u32 s26, 12
	s_cselect_b32 s11, s2, s8
	s_cselect_b32 s10, s3, s0
	s_cselect_b32 s9, s12, s25
	s_cselect_b32 s8, s13, s24
	s_add_i32 m0, s31, 0xc000
	ds_read_b128 v[184:187], v199
	ds_read_b128 v[188:191], v199 offset:1024
	ds_read_b128 v[206:209], v199 offset:2048
	ds_read_b128 v[210:213], v199 offset:3072
	ds_read_b128 v[214:217], v199 offset:4096
	ds_read_b128 v[218:221], v199 offset:5120
	ds_read_b128 v[222:225], v199 offset:6144
	ds_read_b128 v[226:229], v199 offset:7168
	global_load_lds_dwordx4 v180, s[6:7]
	s_add_i32 m0, s31, 0xe000
	s_nop 0
	global_load_lds_dwordx4 v182, s[6:7]
	s_waitcnt vmcnt(8)
	s_waitcnt lgkmcnt(0)
	s_barrier
	s_setprio 1
	s_waitcnt lgkmcnt(0)
	v_mfma_f32_16x16x32_bf16 v[130:133], v[114:117], v[184:187], 0
	v_mfma_f32_16x16x32_bf16 v[126:129], v[138:141], v[184:187], 0
	v_mfma_f32_16x16x32_bf16 v[110:113], v[114:117], v[206:209], 0
	v_mfma_f32_16x16x32_bf16 v[106:109], v[138:141], v[206:209], 0
	v_mfma_f32_16x16x32_bf16 v[94:97], v[114:117], v[214:217], 0
	v_mfma_f32_16x16x32_bf16 v[90:93], v[138:141], v[214:217], 0
	v_mfma_f32_16x16x32_bf16 v[78:81], v[114:117], v[222:225], 0
	v_mfma_f32_16x16x32_bf16 v[74:77], v[138:141], v[222:225], 0
	v_mfma_f32_16x16x32_bf16 v[130:133], v[134:137], v[188:191], v[130:133]
	v_mfma_f32_16x16x32_bf16 v[126:129], v[142:145], v[188:191], v[126:129]
	v_mfma_f32_16x16x32_bf16 v[110:113], v[134:137], v[210:213], v[110:113]
	v_mfma_f32_16x16x32_bf16 v[106:109], v[142:145], v[210:213], v[106:109]
	v_mfma_f32_16x16x32_bf16 v[94:97], v[134:137], v[218:221], v[94:97]
	v_mfma_f32_16x16x32_bf16 v[90:93], v[142:145], v[218:221], v[90:93]
	v_mfma_f32_16x16x32_bf16 v[78:81], v[134:137], v[226:229], v[78:81]
	v_mfma_f32_16x16x32_bf16 v[74:77], v[142:145], v[226:229], v[74:77]
	s_setprio 0
	s_setprio 1
	v_mfma_f32_16x16x32_bf16 v[122:125], v[146:149], v[184:187], 0
	v_mfma_f32_16x16x32_bf16 v[118:121], v[154:157], v[184:187], 0
	v_mfma_f32_16x16x32_bf16 v[102:105], v[146:149], v[206:209], 0
	v_mfma_f32_16x16x32_bf16 v[98:101], v[154:157], v[206:209], 0
	v_mfma_f32_16x16x32_bf16 v[86:89], v[146:149], v[214:217], 0
	v_mfma_f32_16x16x32_bf16 v[82:85], v[154:157], v[214:217], 0
	v_mfma_f32_16x16x32_bf16 v[70:73], v[146:149], v[222:225], 0
	v_mfma_f32_16x16x32_bf16 v[66:69], v[154:157], v[222:225], 0
	v_mfma_f32_16x16x32_bf16 v[122:125], v[150:153], v[188:191], v[122:125]
	v_mfma_f32_16x16x32_bf16 v[118:121], v[158:161], v[188:191], v[118:121]
	v_mfma_f32_16x16x32_bf16 v[102:105], v[150:153], v[210:213], v[102:105]
	v_mfma_f32_16x16x32_bf16 v[98:101], v[158:161], v[210:213], v[98:101]
	v_mfma_f32_16x16x32_bf16 v[86:89], v[150:153], v[218:221], v[86:89]
	v_mfma_f32_16x16x32_bf16 v[82:85], v[158:161], v[218:221], v[82:85]
	v_mfma_f32_16x16x32_bf16 v[70:73], v[150:153], v[226:229], v[70:73]
	v_mfma_f32_16x16x32_bf16 v[66:69], v[158:161], v[226:229], v[66:69]
	s_setprio 0
	s_barrier
	s_add_i32 s0, s89, s79
	s_mov_b32 m0, s0
	ds_read_b128 v[184:187], v199 offset:16384
	ds_read_b128 v[188:191], v199 offset:17408
	ds_read_b128 v[206:209], v199 offset:18432
	ds_read_b128 v[210:213], v199 offset:19456
	ds_read_b128 v[214:217], v199 offset:20480
	ds_read_b128 v[218:221], v199 offset:21504
	ds_read_b128 v[222:225], v199 offset:22528
	ds_read_b128 v[226:229], v199 offset:23552
	global_load_lds_dwordx4 v164, s[8:9]
	s_add_i32 m0, s0, 0x2000
	s_add_u32 s62, s8, 0x40000
	s_addc_u32 s63, s9, 0
	s_add_i32 s0, s90, s79
	global_load_lds_dwordx4 v168, s[8:9]
	s_mov_b32 m0, s0
	s_nop 0
	global_load_lds_dwordx4 v164, s[62:63]
	s_add_i32 m0, s0, 0x2000
	s_nop 0
	global_load_lds_dwordx4 v168, s[62:63]
	s_mov_b32 m0, s31
	s_nop 0
	global_load_lds_dwordx4 v162, s[10:11]
	s_mov_b32 m0, s80
	s_nop 0
	global_load_lds_dwordx4 v166, s[10:11]
	s_waitcnt vmcnt(8)
	s_waitcnt lgkmcnt(0)
	s_barrier
	s_setprio 1
	s_waitcnt lgkmcnt(0)
	v_mfma_f32_16x16x32_bf16 v[62:65], v[114:117], v[184:187], 0
	v_mfma_f32_16x16x32_bf16 v[58:61], v[138:141], v[184:187], 0
	v_mfma_f32_16x16x32_bf16 v[46:49], v[114:117], v[206:209], 0
	v_mfma_f32_16x16x32_bf16 v[42:45], v[138:141], v[206:209], 0
	v_mfma_f32_16x16x32_bf16 v[30:33], v[114:117], v[214:217], 0
	v_mfma_f32_16x16x32_bf16 v[26:29], v[138:141], v[214:217], 0
	v_mfma_f32_16x16x32_bf16 v[14:17], v[114:117], v[222:225], 0
	v_mfma_f32_16x16x32_bf16 v[10:13], v[138:141], v[222:225], 0
	v_mfma_f32_16x16x32_bf16 v[62:65], v[134:137], v[188:191], v[62:65]
	v_mfma_f32_16x16x32_bf16 v[58:61], v[142:145], v[188:191], v[58:61]
	v_mfma_f32_16x16x32_bf16 v[46:49], v[134:137], v[210:213], v[46:49]
	v_mfma_f32_16x16x32_bf16 v[42:45], v[142:145], v[210:213], v[42:45]
	v_mfma_f32_16x16x32_bf16 v[30:33], v[134:137], v[218:221], v[30:33]
	v_mfma_f32_16x16x32_bf16 v[26:29], v[142:145], v[218:221], v[26:29]
	v_mfma_f32_16x16x32_bf16 v[14:17], v[134:137], v[226:229], v[14:17]
	v_mfma_f32_16x16x32_bf16 v[10:13], v[142:145], v[226:229], v[10:13]
	s_setprio 0
	s_setprio 1
	v_mfma_f32_16x16x32_bf16 v[54:57], v[146:149], v[184:187], 0
	v_mfma_f32_16x16x32_bf16 v[50:53], v[154:157], v[184:187], 0
	v_mfma_f32_16x16x32_bf16 v[38:41], v[146:149], v[206:209], 0
	v_mfma_f32_16x16x32_bf16 v[34:37], v[154:157], v[206:209], 0
	v_mfma_f32_16x16x32_bf16 v[22:25], v[146:149], v[214:217], 0
	v_mfma_f32_16x16x32_bf16 v[18:21], v[154:157], v[214:217], 0
	v_mfma_f32_16x16x32_bf16 v[6:9], v[146:149], v[222:225], 0
	v_mfma_f32_16x16x32_bf16 v[2:5], v[154:157], v[222:225], 0
	v_mfma_f32_16x16x32_bf16 v[54:57], v[150:153], v[188:191], v[54:57]
	v_mfma_f32_16x16x32_bf16 v[50:53], v[158:161], v[188:191], v[50:53]
	v_mfma_f32_16x16x32_bf16 v[38:41], v[150:153], v[210:213], v[38:41]
	v_mfma_f32_16x16x32_bf16 v[34:37], v[158:161], v[210:213], v[34:37]
	v_mfma_f32_16x16x32_bf16 v[22:25], v[150:153], v[218:221], v[22:25]
	v_mfma_f32_16x16x32_bf16 v[18:21], v[158:161], v[218:221], v[18:21]
	v_mfma_f32_16x16x32_bf16 v[6:9], v[150:153], v[226:229], v[6:9]
	v_mfma_f32_16x16x32_bf16 v[2:5], v[158:161], v[226:229], v[2:5]
	s_setprio 0
	s_barrier
	s_add_i32 s0, 0, 0x18000
	s_add_i32 s27, 0, 0x1c000
	ds_read_b128 v[114:117], v254
	ds_read_b128 v[134:137], v254 offset:1024
	ds_read_b128 v[138:141], v254 offset:2048
	ds_read_b128 v[142:145], v254 offset:3072
	ds_read_b128 v[146:149], v255
	ds_read_b128 v[150:153], v255 offset:1024
	ds_read_b128 v[154:157], v255 offset:2048
	ds_read_b128 v[158:161], v255 offset:3072
	s_add_u32 s10, s10, 0x40000
	s_addc_u32 s11, s11, 0
	s_mov_b32 m0, s81
	ds_read_b128 v[184:187], v199 offset:32768
	ds_read_b128 v[188:191], v199 offset:33792
	ds_read_b128 v[206:209], v199 offset:34816
	ds_read_b128 v[210:213], v199 offset:35840
	ds_read_b128 v[214:217], v199 offset:36864
	ds_read_b128 v[218:221], v199 offset:37888
	ds_read_b128 v[222:225], v199 offset:38912
	ds_read_b128 v[226:229], v199 offset:39936
	global_load_lds_dwordx4 v162, s[10:11]
	s_mov_b32 m0, s82
	s_nop 0
	global_load_lds_dwordx4 v166, s[10:11]
	s_waitcnt vmcnt(8)
	s_waitcnt lgkmcnt(0)
	s_barrier
	s_setprio 1
	s_waitcnt lgkmcnt(0)
	v_mfma_f32_16x16x32_bf16 v[130:133], v[114:117], v[184:187], v[130:133]
	v_mfma_f32_16x16x32_bf16 v[126:129], v[138:141], v[184:187], v[126:129]
	v_mfma_f32_16x16x32_bf16 v[110:113], v[114:117], v[206:209], v[110:113]
	v_mfma_f32_16x16x32_bf16 v[106:109], v[138:141], v[206:209], v[106:109]
	v_mfma_f32_16x16x32_bf16 v[94:97], v[114:117], v[214:217], v[94:97]
	v_mfma_f32_16x16x32_bf16 v[90:93], v[138:141], v[214:217], v[90:93]
	v_mfma_f32_16x16x32_bf16 v[78:81], v[114:117], v[222:225], v[78:81]
	v_mfma_f32_16x16x32_bf16 v[74:77], v[138:141], v[222:225], v[74:77]
	v_mfma_f32_16x16x32_bf16 v[130:133], v[134:137], v[188:191], v[130:133]
	v_mfma_f32_16x16x32_bf16 v[126:129], v[142:145], v[188:191], v[126:129]
	v_mfma_f32_16x16x32_bf16 v[110:113], v[134:137], v[210:213], v[110:113]
	v_mfma_f32_16x16x32_bf16 v[106:109], v[142:145], v[210:213], v[106:109]
	v_mfma_f32_16x16x32_bf16 v[94:97], v[134:137], v[218:221], v[94:97]
	v_mfma_f32_16x16x32_bf16 v[90:93], v[142:145], v[218:221], v[90:93]
	v_mfma_f32_16x16x32_bf16 v[78:81], v[134:137], v[226:229], v[78:81]
	v_mfma_f32_16x16x32_bf16 v[74:77], v[142:145], v[226:229], v[74:77]
	s_setprio 0
	s_setprio 1
	v_mfma_f32_16x16x32_bf16 v[122:125], v[146:149], v[184:187], v[122:125]
	v_mfma_f32_16x16x32_bf16 v[118:121], v[154:157], v[184:187], v[118:121]
	v_mfma_f32_16x16x32_bf16 v[102:105], v[146:149], v[206:209], v[102:105]
	v_mfma_f32_16x16x32_bf16 v[98:101], v[154:157], v[206:209], v[98:101]
	v_mfma_f32_16x16x32_bf16 v[86:89], v[146:149], v[214:217], v[86:89]
	v_mfma_f32_16x16x32_bf16 v[82:85], v[154:157], v[214:217], v[82:85]
	v_mfma_f32_16x16x32_bf16 v[70:73], v[146:149], v[222:225], v[70:73]
	v_mfma_f32_16x16x32_bf16 v[66:69], v[154:157], v[222:225], v[66:69]
	v_mfma_f32_16x16x32_bf16 v[122:125], v[150:153], v[188:191], v[122:125]
	v_mfma_f32_16x16x32_bf16 v[118:121], v[158:161], v[188:191], v[118:121]
	v_mfma_f32_16x16x32_bf16 v[102:105], v[150:153], v[210:213], v[102:105]
	v_mfma_f32_16x16x32_bf16 v[98:101], v[158:161], v[210:213], v[98:101]
	v_mfma_f32_16x16x32_bf16 v[86:89], v[150:153], v[218:221], v[86:89]
	v_mfma_f32_16x16x32_bf16 v[82:85], v[158:161], v[218:221], v[82:85]
	v_mfma_f32_16x16x32_bf16 v[70:73], v[150:153], v[226:229], v[70:73]
	v_mfma_f32_16x16x32_bf16 v[66:69], v[158:161], v[226:229], v[66:69]
	s_setprio 0
	s_barrier
	s_add_i32 s0, s0, s79
	s_mov_b32 m0, s0
	ds_read_b128 v[184:187], v199 offset:49152
	ds_read_b128 v[188:191], v199 offset:50176
	ds_read_b128 v[206:209], v199 offset:51200
	ds_read_b128 v[210:213], v199 offset:52224
	ds_read_b128 v[214:217], v199 offset:53248
	ds_read_b128 v[218:221], v199 offset:54272
	ds_read_b128 v[222:225], v199 offset:55296
	ds_read_b128 v[226:229], v199 offset:56320
	s_add_u32 s98, s8, 0x80
	s_addc_u32 s99, s9, 0
	global_load_lds_dwordx4 v164, s[98:99]
	s_add_i32 m0, s0, 0x2000
	s_add_u32 s8, s8, 0x40080
	s_addc_u32 s9, s9, 0
	s_add_i32 s0, s27, s79
	global_load_lds_dwordx4 v168, s[98:99]
	s_mov_b32 m0, s0
	s_nop 0
	global_load_lds_dwordx4 v164, s[8:9]
	s_add_i32 m0, s0, 0x2000
	s_nop 0
	global_load_lds_dwordx4 v168, s[8:9]
	s_add_u32 s98, s10, 0xfffc0080
	s_addc_u32 s99, s11, -1
	s_mov_b32 m0, s84
	s_nop 0
	global_load_lds_dwordx4 v162, s[98:99]
	s_mov_b32 m0, s85
	s_nop 0
	global_load_lds_dwordx4 v166, s[98:99]
	s_waitcnt vmcnt(8)
	s_waitcnt lgkmcnt(0)
	s_barrier
	s_setprio 1
	s_waitcnt lgkmcnt(0)
	v_mfma_f32_16x16x32_bf16 v[62:65], v[114:117], v[184:187], v[62:65]
	v_mfma_f32_16x16x32_bf16 v[58:61], v[138:141], v[184:187], v[58:61]
	v_mfma_f32_16x16x32_bf16 v[46:49], v[114:117], v[206:209], v[46:49]
	v_mfma_f32_16x16x32_bf16 v[42:45], v[138:141], v[206:209], v[42:45]
	v_mfma_f32_16x16x32_bf16 v[30:33], v[114:117], v[214:217], v[30:33]
	v_mfma_f32_16x16x32_bf16 v[26:29], v[138:141], v[214:217], v[26:29]
	v_mfma_f32_16x16x32_bf16 v[14:17], v[114:117], v[222:225], v[14:17]
	v_mfma_f32_16x16x32_bf16 v[10:13], v[138:141], v[222:225], v[10:13]
	v_mfma_f32_16x16x32_bf16 v[62:65], v[134:137], v[188:191], v[62:65]
	v_mfma_f32_16x16x32_bf16 v[58:61], v[142:145], v[188:191], v[58:61]
	v_mfma_f32_16x16x32_bf16 v[46:49], v[134:137], v[210:213], v[46:49]
	v_mfma_f32_16x16x32_bf16 v[42:45], v[142:145], v[210:213], v[42:45]
	v_mfma_f32_16x16x32_bf16 v[30:33], v[134:137], v[218:221], v[30:33]
	v_mfma_f32_16x16x32_bf16 v[26:29], v[142:145], v[218:221], v[26:29]
	v_mfma_f32_16x16x32_bf16 v[14:17], v[134:137], v[226:229], v[14:17]
	v_mfma_f32_16x16x32_bf16 v[10:13], v[142:145], v[226:229], v[10:13]
	s_setprio 0
	s_setprio 1
	v_mfma_f32_16x16x32_bf16 v[54:57], v[146:149], v[184:187], v[54:57]
	v_mfma_f32_16x16x32_bf16 v[50:53], v[154:157], v[184:187], v[50:53]
	v_mfma_f32_16x16x32_bf16 v[38:41], v[146:149], v[206:209], v[38:41]
	v_mfma_f32_16x16x32_bf16 v[34:37], v[154:157], v[206:209], v[34:37]
	v_mfma_f32_16x16x32_bf16 v[22:25], v[146:149], v[214:217], v[22:25]
	v_mfma_f32_16x16x32_bf16 v[18:21], v[154:157], v[214:217], v[18:21]
	v_mfma_f32_16x16x32_bf16 v[6:9], v[146:149], v[222:225], v[6:9]
	v_mfma_f32_16x16x32_bf16 v[2:5], v[154:157], v[222:225], v[2:5]
	v_mfma_f32_16x16x32_bf16 v[54:57], v[150:153], v[188:191], v[54:57]
	v_mfma_f32_16x16x32_bf16 v[50:53], v[158:161], v[188:191], v[50:53]
	v_mfma_f32_16x16x32_bf16 v[38:41], v[150:153], v[210:213], v[38:41]
	v_mfma_f32_16x16x32_bf16 v[34:37], v[158:161], v[210:213], v[34:37]
	v_mfma_f32_16x16x32_bf16 v[22:25], v[150:153], v[218:221], v[22:25]
	v_mfma_f32_16x16x32_bf16 v[18:21], v[158:161], v[218:221], v[18:21]
	v_mfma_f32_16x16x32_bf16 v[6:9], v[150:153], v[226:229], v[6:9]
	v_mfma_f32_16x16x32_bf16 v[2:5], v[158:161], v[226:229], v[2:5]
	s_setprio 0
	s_barrier
	s_add_i32 s26, s26, 2
	s_add_u32 s6, s6, 0x100
	s_addc_u32 s7, s7, 0
	s_add_u32 s24, s24, 0x100
	s_addc_u32 s25, s25, 0
	s_cmp_gt_u32 s26, 13
	s_cbranch_scc1 .Lpeel_x1
.LBB0_368:
	ds_read_b128 v[114:117], v197
	ds_read_b128 v[134:137], v197 offset:1024
	ds_read_b128 v[138:141], v197 offset:2048
	ds_read_b128 v[142:145], v197 offset:3072
	ds_read_b128 v[146:149], v198
	ds_read_b128 v[150:153], v198 offset:1024
	ds_read_b128 v[154:157], v198 offset:2048
	ds_read_b128 v[158:161], v198 offset:3072
	s_add_u32 s0, s6, 0xfffc0080
	s_addc_u32 s8, s7, -1
	s_cmp_eq_u32 s26, 12
	s_cselect_b32 s11, s2, s8
	s_cselect_b32 s10, s3, s0
	s_cselect_b32 s9, s12, s25
	s_cselect_b32 s8, s13, s24
	s_add_i32 m0, s31, 0xc000
	ds_read_b128 v[184:187], v199
	ds_read_b128 v[188:191], v199 offset:1024
	ds_read_b128 v[206:209], v199 offset:2048
	ds_read_b128 v[210:213], v199 offset:3072
	ds_read_b128 v[214:217], v199 offset:4096
	ds_read_b128 v[218:221], v199 offset:5120
	ds_read_b128 v[222:225], v199 offset:6144
	ds_read_b128 v[226:229], v199 offset:7168
	global_load_lds_dwordx4 v180, s[6:7]
	s_add_i32 m0, s31, 0xe000
	s_nop 0
	global_load_lds_dwordx4 v182, s[6:7]
	s_waitcnt vmcnt(8)
	s_waitcnt lgkmcnt(0)
	s_barrier
	s_setprio 1
	s_waitcnt lgkmcnt(0)
	v_mfma_f32_16x16x32_bf16 v[130:133], v[114:117], v[184:187], v[130:133]
	v_mfma_f32_16x16x32_bf16 v[126:129], v[138:141], v[184:187], v[126:129]
	v_mfma_f32_16x16x32_bf16 v[110:113], v[114:117], v[206:209], v[110:113]
	v_mfma_f32_16x16x32_bf16 v[106:109], v[138:141], v[206:209], v[106:109]
	v_mfma_f32_16x16x32_bf16 v[94:97], v[114:117], v[214:217], v[94:97]
	v_mfma_f32_16x16x32_bf16 v[90:93], v[138:141], v[214:217], v[90:93]
	v_mfma_f32_16x16x32_bf16 v[78:81], v[114:117], v[222:225], v[78:81]
	v_mfma_f32_16x16x32_bf16 v[74:77], v[138:141], v[222:225], v[74:77]
	v_mfma_f32_16x16x32_bf16 v[130:133], v[134:137], v[188:191], v[130:133]
	v_mfma_f32_16x16x32_bf16 v[126:129], v[142:145], v[188:191], v[126:129]
	v_mfma_f32_16x16x32_bf16 v[110:113], v[134:137], v[210:213], v[110:113]
	v_mfma_f32_16x16x32_bf16 v[106:109], v[142:145], v[210:213], v[106:109]
	v_mfma_f32_16x16x32_bf16 v[94:97], v[134:137], v[218:221], v[94:97]
	v_mfma_f32_16x16x32_bf16 v[90:93], v[142:145], v[218:221], v[90:93]
	v_mfma_f32_16x16x32_bf16 v[78:81], v[134:137], v[226:229], v[78:81]
	v_mfma_f32_16x16x32_bf16 v[74:77], v[142:145], v[226:229], v[74:77]
	s_setprio 0
	s_setprio 1
	v_mfma_f32_16x16x32_bf16 v[122:125], v[146:149], v[184:187], v[122:125]
	v_mfma_f32_16x16x32_bf16 v[118:121], v[154:157], v[184:187], v[118:121]
	v_mfma_f32_16x16x32_bf16 v[102:105], v[146:149], v[206:209], v[102:105]
	v_mfma_f32_16x16x32_bf16 v[98:101], v[154:157], v[206:209], v[98:101]
	v_mfma_f32_16x16x32_bf16 v[86:89], v[146:149], v[214:217], v[86:89]
	v_mfma_f32_16x16x32_bf16 v[82:85], v[154:157], v[214:217], v[82:85]
	v_mfma_f32_16x16x32_bf16 v[70:73], v[146:149], v[222:225], v[70:73]
	v_mfma_f32_16x16x32_bf16 v[66:69], v[154:157], v[222:225], v[66:69]
	v_mfma_f32_16x16x32_bf16 v[122:125], v[150:153], v[188:191], v[122:125]
	v_mfma_f32_16x16x32_bf16 v[118:121], v[158:161], v[188:191], v[118:121]
	v_mfma_f32_16x16x32_bf16 v[102:105], v[150:153], v[210:213], v[102:105]
	v_mfma_f32_16x16x32_bf16 v[98:101], v[158:161], v[210:213], v[98:101]
	v_mfma_f32_16x16x32_bf16 v[86:89], v[150:153], v[218:221], v[86:89]
	v_mfma_f32_16x16x32_bf16 v[82:85], v[158:161], v[218:221], v[82:85]
	v_mfma_f32_16x16x32_bf16 v[70:73], v[150:153], v[226:229], v[70:73]
	v_mfma_f32_16x16x32_bf16 v[66:69], v[158:161], v[226:229], v[66:69]
	s_setprio 0
	s_barrier
	s_add_i32 s0, s89, s79
	s_mov_b32 m0, s0
	ds_read_b128 v[184:187], v199 offset:16384
	ds_read_b128 v[188:191], v199 offset:17408
	ds_read_b128 v[206:209], v199 offset:18432
	ds_read_b128 v[210:213], v199 offset:19456
	ds_read_b128 v[214:217], v199 offset:20480
	ds_read_b128 v[218:221], v199 offset:21504
	ds_read_b128 v[222:225], v199 offset:22528
	ds_read_b128 v[226:229], v199 offset:23552
	global_load_lds_dwordx4 v164, s[8:9]
	s_add_i32 m0, s0, 0x2000
	s_add_u32 s62, s8, 0x40000
	s_addc_u32 s63, s9, 0
	s_add_i32 s0, s90, s79
	global_load_lds_dwordx4 v168, s[8:9]
	s_mov_b32 m0, s0
	s_nop 0
	global_load_lds_dwordx4 v164, s[62:63]
	s_add_i32 m0, s0, 0x2000
	s_nop 0
	global_load_lds_dwordx4 v168, s[62:63]
	s_mov_b32 m0, s31
	s_nop 0
	global_load_lds_dwordx4 v162, s[10:11]
	s_mov_b32 m0, s80
	s_nop 0
	global_load_lds_dwordx4 v166, s[10:11]
	s_waitcnt vmcnt(8)
	s_waitcnt lgkmcnt(0)
	s_barrier
	s_setprio 1
	s_waitcnt lgkmcnt(0)
	v_mfma_f32_16x16x32_bf16 v[62:65], v[114:117], v[184:187], v[62:65]
	v_mfma_f32_16x16x32_bf16 v[58:61], v[138:141], v[184:187], v[58:61]
	v_mfma_f32_16x16x32_bf16 v[46:49], v[114:117], v[206:209], v[46:49]
	v_mfma_f32_16x16x32_bf16 v[42:45], v[138:141], v[206:209], v[42:45]
	v_mfma_f32_16x16x32_bf16 v[30:33], v[114:117], v[214:217], v[30:33]
	v_mfma_f32_16x16x32_bf16 v[26:29], v[138:141], v[214:217], v[26:29]
	v_mfma_f32_16x16x32_bf16 v[14:17], v[114:117], v[222:225], v[14:17]
	v_mfma_f32_16x16x32_bf16 v[10:13], v[138:141], v[222:225], v[10:13]
	v_mfma_f32_16x16x32_bf16 v[62:65], v[134:137], v[188:191], v[62:65]
	v_mfma_f32_16x16x32_bf16 v[58:61], v[142:145], v[188:191], v[58:61]
	v_mfma_f32_16x16x32_bf16 v[46:49], v[134:137], v[210:213], v[46:49]
	v_mfma_f32_16x16x32_bf16 v[42:45], v[142:145], v[210:213], v[42:45]
	v_mfma_f32_16x16x32_bf16 v[30:33], v[134:137], v[218:221], v[30:33]
	v_mfma_f32_16x16x32_bf16 v[26:29], v[142:145], v[218:221], v[26:29]
	v_mfma_f32_16x16x32_bf16 v[14:17], v[134:137], v[226:229], v[14:17]
	v_mfma_f32_16x16x32_bf16 v[10:13], v[142:145], v[226:229], v[10:13]
	s_setprio 0
	s_setprio 1
	v_mfma_f32_16x16x32_bf16 v[54:57], v[146:149], v[184:187], v[54:57]
	v_mfma_f32_16x16x32_bf16 v[50:53], v[154:157], v[184:187], v[50:53]
	v_mfma_f32_16x16x32_bf16 v[38:41], v[146:149], v[206:209], v[38:41]
	v_mfma_f32_16x16x32_bf16 v[34:37], v[154:157], v[206:209], v[34:37]
	v_mfma_f32_16x16x32_bf16 v[22:25], v[146:149], v[214:217], v[22:25]
	v_mfma_f32_16x16x32_bf16 v[18:21], v[154:157], v[214:217], v[18:21]
	v_mfma_f32_16x16x32_bf16 v[6:9], v[146:149], v[222:225], v[6:9]
	v_mfma_f32_16x16x32_bf16 v[2:5], v[154:157], v[222:225], v[2:5]
	v_mfma_f32_16x16x32_bf16 v[54:57], v[150:153], v[188:191], v[54:57]
	v_mfma_f32_16x16x32_bf16 v[50:53], v[158:161], v[188:191], v[50:53]
	v_mfma_f32_16x16x32_bf16 v[38:41], v[150:153], v[210:213], v[38:41]
	v_mfma_f32_16x16x32_bf16 v[34:37], v[158:161], v[210:213], v[34:37]
	v_mfma_f32_16x16x32_bf16 v[22:25], v[150:153], v[218:221], v[22:25]
	v_mfma_f32_16x16x32_bf16 v[18:21], v[158:161], v[218:221], v[18:21]
	v_mfma_f32_16x16x32_bf16 v[6:9], v[150:153], v[226:229], v[6:9]
	v_mfma_f32_16x16x32_bf16 v[2:5], v[158:161], v[226:229], v[2:5]
	s_setprio 0
	s_barrier
	s_add_i32 s0, 0, 0x18000
	s_add_i32 s27, 0, 0x1c000
	ds_read_b128 v[114:117], v254
	ds_read_b128 v[134:137], v254 offset:1024
	ds_read_b128 v[138:141], v254 offset:2048
	ds_read_b128 v[142:145], v254 offset:3072
	ds_read_b128 v[146:149], v255
	ds_read_b128 v[150:153], v255 offset:1024
	ds_read_b128 v[154:157], v255 offset:2048
	ds_read_b128 v[158:161], v255 offset:3072
	s_add_u32 s10, s10, 0x40000
	s_addc_u32 s11, s11, 0
	s_mov_b32 m0, s81
	ds_read_b128 v[184:187], v199 offset:32768
	ds_read_b128 v[188:191], v199 offset:33792
	ds_read_b128 v[206:209], v199 offset:34816
	ds_read_b128 v[210:213], v199 offset:35840
	ds_read_b128 v[214:217], v199 offset:36864
	ds_read_b128 v[218:221], v199 offset:37888
	ds_read_b128 v[222:225], v199 offset:38912
	ds_read_b128 v[226:229], v199 offset:39936
	global_load_lds_dwordx4 v162, s[10:11]
	s_mov_b32 m0, s82
	s_nop 0
	global_load_lds_dwordx4 v166, s[10:11]
	s_waitcnt vmcnt(8)
	s_waitcnt lgkmcnt(0)
	s_barrier
	s_setprio 1
	s_waitcnt lgkmcnt(0)
	v_mfma_f32_16x16x32_bf16 v[130:133], v[114:117], v[184:187], v[130:133]
	v_mfma_f32_16x16x32_bf16 v[126:129], v[138:141], v[184:187], v[126:129]
	v_mfma_f32_16x16x32_bf16 v[110:113], v[114:117], v[206:209], v[110:113]
	v_mfma_f32_16x16x32_bf16 v[106:109], v[138:141], v[206:209], v[106:109]
	v_mfma_f32_16x16x32_bf16 v[94:97], v[114:117], v[214:217], v[94:97]
	v_mfma_f32_16x16x32_bf16 v[90:93], v[138:141], v[214:217], v[90:93]
	v_mfma_f32_16x16x32_bf16 v[78:81], v[114:117], v[222:225], v[78:81]
	v_mfma_f32_16x16x32_bf16 v[74:77], v[138:141], v[222:225], v[74:77]
	v_mfma_f32_16x16x32_bf16 v[130:133], v[134:137], v[188:191], v[130:133]
	v_mfma_f32_16x16x32_bf16 v[126:129], v[142:145], v[188:191], v[126:129]
	v_mfma_f32_16x16x32_bf16 v[110:113], v[134:137], v[210:213], v[110:113]
	v_mfma_f32_16x16x32_bf16 v[106:109], v[142:145], v[210:213], v[106:109]
	v_mfma_f32_16x16x32_bf16 v[94:97], v[134:137], v[218:221], v[94:97]
	v_mfma_f32_16x16x32_bf16 v[90:93], v[142:145], v[218:221], v[90:93]
	v_mfma_f32_16x16x32_bf16 v[78:81], v[134:137], v[226:229], v[78:81]
	v_mfma_f32_16x16x32_bf16 v[74:77], v[142:145], v[226:229], v[74:77]
	s_setprio 0
	s_setprio 1
	v_mfma_f32_16x16x32_bf16 v[122:125], v[146:149], v[184:187], v[122:125]
	v_mfma_f32_16x16x32_bf16 v[118:121], v[154:157], v[184:187], v[118:121]
	v_mfma_f32_16x16x32_bf16 v[102:105], v[146:149], v[206:209], v[102:105]
	v_mfma_f32_16x16x32_bf16 v[98:101], v[154:157], v[206:209], v[98:101]
	v_mfma_f32_16x16x32_bf16 v[86:89], v[146:149], v[214:217], v[86:89]
	v_mfma_f32_16x16x32_bf16 v[82:85], v[154:157], v[214:217], v[82:85]
	v_mfma_f32_16x16x32_bf16 v[70:73], v[146:149], v[222:225], v[70:73]
	v_mfma_f32_16x16x32_bf16 v[66:69], v[154:157], v[222:225], v[66:69]
	v_mfma_f32_16x16x32_bf16 v[122:125], v[150:153], v[188:191], v[122:125]
	v_mfma_f32_16x16x32_bf16 v[118:121], v[158:161], v[188:191], v[118:121]
	v_mfma_f32_16x16x32_bf16 v[102:105], v[150:153], v[210:213], v[102:105]
	v_mfma_f32_16x16x32_bf16 v[98:101], v[158:161], v[210:213], v[98:101]
	v_mfma_f32_16x16x32_bf16 v[86:89], v[150:153], v[218:221], v[86:89]
	v_mfma_f32_16x16x32_bf16 v[82:85], v[158:161], v[218:221], v[82:85]
	v_mfma_f32_16x16x32_bf16 v[70:73], v[150:153], v[226:229], v[70:73]
	v_mfma_f32_16x16x32_bf16 v[66:69], v[158:161], v[226:229], v[66:69]
	s_setprio 0
	s_barrier
	s_add_i32 s0, s0, s79
	s_mov_b32 m0, s0
	ds_read_b128 v[184:187], v199 offset:49152
	ds_read_b128 v[188:191], v199 offset:50176
	ds_read_b128 v[206:209], v199 offset:51200
	ds_read_b128 v[210:213], v199 offset:52224
	ds_read_b128 v[214:217], v199 offset:53248
	ds_read_b128 v[218:221], v199 offset:54272
	ds_read_b128 v[222:225], v199 offset:55296
	ds_read_b128 v[226:229], v199 offset:56320
	s_add_u32 s98, s8, 0x80
	s_addc_u32 s99, s9, 0
	global_load_lds_dwordx4 v164, s[98:99]
	s_add_i32 m0, s0, 0x2000
	s_add_u32 s8, s8, 0x40080
	s_addc_u32 s9, s9, 0
	s_add_i32 s0, s27, s79
	global_load_lds_dwordx4 v168, s[98:99]
	s_mov_b32 m0, s0
	s_nop 0
	global_load_lds_dwordx4 v164, s[8:9]
	s_add_i32 m0, s0, 0x2000
	s_nop 0
	global_load_lds_dwordx4 v168, s[8:9]
	s_add_u32 s98, s10, 0xfffc0080
	s_addc_u32 s99, s11, -1
	s_mov_b32 m0, s84
	s_nop 0
	global_load_lds_dwordx4 v162, s[98:99]
	s_mov_b32 m0, s85
	s_nop 0
	global_load_lds_dwordx4 v166, s[98:99]
	s_waitcnt vmcnt(8)
	s_waitcnt lgkmcnt(0)
	s_barrier
	s_setprio 1
	s_waitcnt lgkmcnt(0)
	v_mfma_f32_16x16x32_bf16 v[62:65], v[114:117], v[184:187], v[62:65]
	v_mfma_f32_16x16x32_bf16 v[58:61], v[138:141], v[184:187], v[58:61]
	v_mfma_f32_16x16x32_bf16 v[46:49], v[114:117], v[206:209], v[46:49]
	v_mfma_f32_16x16x32_bf16 v[42:45], v[138:141], v[206:209], v[42:45]
	v_mfma_f32_16x16x32_bf16 v[30:33], v[114:117], v[214:217], v[30:33]
	v_mfma_f32_16x16x32_bf16 v[26:29], v[138:141], v[214:217], v[26:29]
	v_mfma_f32_16x16x32_bf16 v[14:17], v[114:117], v[222:225], v[14:17]
	v_mfma_f32_16x16x32_bf16 v[10:13], v[138:141], v[222:225], v[10:13]
	v_mfma_f32_16x16x32_bf16 v[62:65], v[134:137], v[188:191], v[62:65]
	v_mfma_f32_16x16x32_bf16 v[58:61], v[142:145], v[188:191], v[58:61]
	v_mfma_f32_16x16x32_bf16 v[46:49], v[134:137], v[210:213], v[46:49]
	v_mfma_f32_16x16x32_bf16 v[42:45], v[142:145], v[210:213], v[42:45]
	v_mfma_f32_16x16x32_bf16 v[30:33], v[134:137], v[218:221], v[30:33]
	v_mfma_f32_16x16x32_bf16 v[26:29], v[142:145], v[218:221], v[26:29]
	v_mfma_f32_16x16x32_bf16 v[14:17], v[134:137], v[226:229], v[14:17]
	v_mfma_f32_16x16x32_bf16 v[10:13], v[142:145], v[226:229], v[10:13]
	s_setprio 0
	s_setprio 1
	v_mfma_f32_16x16x32_bf16 v[54:57], v[146:149], v[184:187], v[54:57]
	v_mfma_f32_16x16x32_bf16 v[50:53], v[154:157], v[184:187], v[50:53]
	v_mfma_f32_16x16x32_bf16 v[38:41], v[146:149], v[206:209], v[38:41]
	v_mfma_f32_16x16x32_bf16 v[34:37], v[154:157], v[206:209], v[34:37]
	v_mfma_f32_16x16x32_bf16 v[22:25], v[146:149], v[214:217], v[22:25]
	v_mfma_f32_16x16x32_bf16 v[18:21], v[154:157], v[214:217], v[18:21]
	v_mfma_f32_16x16x32_bf16 v[6:9], v[146:149], v[222:225], v[6:9]
	v_mfma_f32_16x16x32_bf16 v[2:5], v[154:157], v[222:225], v[2:5]
	v_mfma_f32_16x16x32_bf16 v[54:57], v[150:153], v[188:191], v[54:57]
	v_mfma_f32_16x16x32_bf16 v[50:53], v[158:161], v[188:191], v[50:53]
	v_mfma_f32_16x16x32_bf16 v[38:41], v[150:153], v[210:213], v[38:41]
	v_mfma_f32_16x16x32_bf16 v[34:37], v[158:161], v[210:213], v[34:37]
	v_mfma_f32_16x16x32_bf16 v[22:25], v[150:153], v[218:221], v[22:25]
	v_mfma_f32_16x16x32_bf16 v[18:21], v[158:161], v[218:221], v[18:21]
	v_mfma_f32_16x16x32_bf16 v[6:9], v[150:153], v[226:229], v[6:9]
	v_mfma_f32_16x16x32_bf16 v[2:5], v[158:161], v[226:229], v[2:5]
	s_setprio 0
	s_barrier
	s_add_i32 s26, s26, 2
	s_add_u32 s6, s6, 0x100
	s_addc_u32 s7, s7, 0
	s_add_u32 s24, s24, 0x100
	s_addc_u32 s25, s25, 0
	s_cmp_gt_u32 s26, 13
	s_cbranch_scc0 .LBB0_368

.LBB0_902:
	s_mov_b64 s[28:29], s[10:11]
	s_mov_b32 s10, s37
	s_mov_b32 s0, s37
	s_add_i32 s37, s47, s1
	s_mov_b64 s[30:31], s[8:9]
	s_and_b64 s[8:9], s[26:27], exec
	s_cselect_b32 s8, s37, s10
	s_cselect_b32 s10, s46, s46
	s_ashr_i32 s11, s10, 31
	s_lshl_b64 s[10:11], s[10:11], 19
	s_add_u32 s10, s2, s10
	s_addc_u32 s11, s3, s11
	s_and_b64 s[34:35], s[26:27], exec
	s_cselect_b32 s1, s11, s29
	s_cselect_b32 s50, s10, s28
	s_ashr_i32 s9, s8, 31
	s_lshl_b64 s[8:9], s[8:9], 19
	s_add_u32 s8, s4, s8
	s_addc_u32 s9, s5, s9
	s_and_b64 s[34:35], s[26:27], exec
	s_cselect_b32 s51, s9, s31
	s_cselect_b32 s52, s8, s30
	s_add_u32 s28, s28, 0x40080
	s_addc_u32 s29, s29, 0
	s_add_u32 s53, s30, 0x100
	s_addc_u32 s54, s31, 0
	s_mov_b32 s55, -2
	s_waitcnt lgkmcnt(0)
	v_add_u32_e32 v254, 0x18000, v207
	v_add_u32_e32 v255, 0x1c000, v207
	ds_read_b128 v[130:133], v209
	ds_read_b128 v[134:137], v209 offset:1024
	ds_read_b128 v[138:141], v209 offset:2048
	ds_read_b128 v[142:145], v209 offset:3072
	ds_read_b128 v[146:149], v210
	ds_read_b128 v[150:153], v210 offset:1024
	ds_read_b128 v[154:157], v210 offset:2048
	ds_read_b128 v[158:161], v210 offset:3072
	s_add_u32 s30, s28, 0xfffc0080
	s_addc_u32 s31, s29, -1
	s_cmp_eq_u32 s55, 12
	s_cselect_b32 s35, s1, s31
	s_cselect_b32 s34, s50, s30
	s_cselect_b32 s31, s51, s54
	s_cselect_b32 s30, s52, s53
	v_lshl_add_u64 v[216:217], s[28:29], 0, v[190:191]
	s_add_i32 m0, s39, 0xc000
	ds_read_b128 v[162:165], v211
	ds_read_b128 v[166:169], v211 offset:1024
	ds_read_b128 v[170:173], v211 offset:2048
	ds_read_b128 v[174:177], v211 offset:3072
	ds_read_b128 v[194:197], v211 offset:4096
	ds_read_b128 v[198:201], v211 offset:5120
	ds_read_b128 v[202:205], v211 offset:6144
	ds_read_b128 v[212:215], v211 offset:7168
	global_load_lds_dwordx4 v[216:217], off
	v_lshl_add_u64 v[216:217], s[28:29], 0, v[192:193]
	s_add_i32 m0, s39, 0xe000
	s_nop 0
	global_load_lds_dwordx4 v[216:217], off
	s_waitcnt vmcnt(8)
	s_waitcnt lgkmcnt(0)
	s_barrier
	s_setprio 1
	s_waitcnt lgkmcnt(0)
	v_mfma_f32_16x16x32_bf16 v[126:129], v[130:133], v[162:165], 0
	v_mfma_f32_16x16x32_bf16 v[122:125], v[138:141], v[162:165], 0
	v_mfma_f32_16x16x32_bf16 v[110:113], v[130:133], v[170:173], 0
	v_mfma_f32_16x16x32_bf16 v[106:109], v[138:141], v[170:173], 0
	v_mfma_f32_16x16x32_bf16 v[94:97], v[130:133], v[194:197], 0
	v_mfma_f32_16x16x32_bf16 v[90:93], v[138:141], v[194:197], 0
	v_mfma_f32_16x16x32_bf16 v[78:81], v[130:133], v[202:205], 0
	v_mfma_f32_16x16x32_bf16 v[74:77], v[138:141], v[202:205], 0
	v_mfma_f32_16x16x32_bf16 v[126:129], v[134:137], v[166:169], v[126:129]
	v_mfma_f32_16x16x32_bf16 v[122:125], v[142:145], v[166:169], v[122:125]
	v_mfma_f32_16x16x32_bf16 v[110:113], v[134:137], v[174:177], v[110:113]
	v_mfma_f32_16x16x32_bf16 v[106:109], v[142:145], v[174:177], v[106:109]
	v_mfma_f32_16x16x32_bf16 v[94:97], v[134:137], v[198:201], v[94:97]
	v_mfma_f32_16x16x32_bf16 v[90:93], v[142:145], v[198:201], v[90:93]
	v_mfma_f32_16x16x32_bf16 v[78:81], v[134:137], v[212:215], v[78:81]
	v_mfma_f32_16x16x32_bf16 v[74:77], v[142:145], v[212:215], v[74:77]
	s_setprio 0
	s_setprio 1
	v_mfma_f32_16x16x32_bf16 v[118:121], v[146:149], v[162:165], 0
	v_mfma_f32_16x16x32_bf16 v[114:117], v[154:157], v[162:165], 0
	v_mfma_f32_16x16x32_bf16 v[102:105], v[146:149], v[170:173], 0
	v_mfma_f32_16x16x32_bf16 v[98:101], v[154:157], v[170:173], 0
	v_mfma_f32_16x16x32_bf16 v[86:89], v[146:149], v[194:197], 0
	v_mfma_f32_16x16x32_bf16 v[82:85], v[154:157], v[194:197], 0
	v_mfma_f32_16x16x32_bf16 v[70:73], v[146:149], v[202:205], 0
	v_mfma_f32_16x16x32_bf16 v[66:69], v[154:157], v[202:205], 0
	v_mfma_f32_16x16x32_bf16 v[118:121], v[150:153], v[166:169], v[118:121]
	v_mfma_f32_16x16x32_bf16 v[114:117], v[158:161], v[166:169], v[114:117]
	v_mfma_f32_16x16x32_bf16 v[102:105], v[150:153], v[174:177], v[102:105]
	v_mfma_f32_16x16x32_bf16 v[98:101], v[158:161], v[174:177], v[98:101]
	v_mfma_f32_16x16x32_bf16 v[86:89], v[150:153], v[198:201], v[86:89]
	v_mfma_f32_16x16x32_bf16 v[82:85], v[158:161], v[198:201], v[82:85]
	v_mfma_f32_16x16x32_bf16 v[70:73], v[150:153], v[212:215], v[70:73]
	v_mfma_f32_16x16x32_bf16 v[66:69], v[158:161], v[212:215], v[66:69]
	s_setprio 0
	s_barrier
	s_add_i32 s56, s48, s38
	v_lshl_add_u64 v[216:217], s[30:31], 0, v[184:185]
	s_mov_b32 m0, s56
	ds_read_b128 v[162:165], v211 offset:16384
	ds_read_b128 v[166:169], v211 offset:17408
	ds_read_b128 v[170:173], v211 offset:18432
	ds_read_b128 v[174:177], v211 offset:19456
	ds_read_b128 v[194:197], v211 offset:20480
	ds_read_b128 v[198:201], v211 offset:21504
	ds_read_b128 v[202:205], v211 offset:22528
	ds_read_b128 v[212:215], v211 offset:23552
	global_load_lds_dwordx4 v[216:217], off
	s_add_i32 m0, s56, 0x2000
	s_add_u32 s56, s30, 0x40000
	v_lshl_add_u64 v[218:219], s[30:31], 0, v[188:189]
	s_addc_u32 s57, s31, 0
	s_add_i32 s58, s49, s38
	global_load_lds_dwordx4 v[218:219], off
	v_lshl_add_u64 v[220:221], s[56:57], 0, v[184:185]
	s_mov_b32 m0, s58
	v_lshl_add_u64 v[222:223], s[34:35], 0, v[186:187]
	global_load_lds_dwordx4 v[220:221], off
	v_lshl_add_u64 v[220:221], s[56:57], 0, v[188:189]
	s_add_i32 m0, s58, 0x2000
	s_nop 0
	global_load_lds_dwordx4 v[220:221], off
	v_lshl_add_u64 v[220:221], s[34:35], 0, v[182:183]
	s_mov_b32 m0, s39
	s_nop 0
	global_load_lds_dwordx4 v[220:221], off
	s_mov_b32 m0, s40
	s_nop 0
	global_load_lds_dwordx4 v[222:223], off
	s_waitcnt vmcnt(8)
	s_waitcnt lgkmcnt(0)
	s_barrier
	s_setprio 1
	s_waitcnt lgkmcnt(0)
	v_mfma_f32_16x16x32_bf16 v[62:65], v[130:133], v[162:165], 0
	v_mfma_f32_16x16x32_bf16 v[58:61], v[138:141], v[162:165], 0
	v_mfma_f32_16x16x32_bf16 v[46:49], v[130:133], v[170:173], 0
	v_mfma_f32_16x16x32_bf16 v[42:45], v[138:141], v[170:173], 0
	v_mfma_f32_16x16x32_bf16 v[30:33], v[130:133], v[194:197], 0
	v_mfma_f32_16x16x32_bf16 v[26:29], v[138:141], v[194:197], 0
	v_mfma_f32_16x16x32_bf16 v[14:17], v[130:133], v[202:205], 0
	v_mfma_f32_16x16x32_bf16 v[10:13], v[138:141], v[202:205], 0
	v_mfma_f32_16x16x32_bf16 v[62:65], v[134:137], v[166:169], v[62:65]
	v_mfma_f32_16x16x32_bf16 v[58:61], v[142:145], v[166:169], v[58:61]
	v_mfma_f32_16x16x32_bf16 v[46:49], v[134:137], v[174:177], v[46:49]
	v_mfma_f32_16x16x32_bf16 v[42:45], v[142:145], v[174:177], v[42:45]
	v_mfma_f32_16x16x32_bf16 v[30:33], v[134:137], v[198:201], v[30:33]
	v_mfma_f32_16x16x32_bf16 v[26:29], v[142:145], v[198:201], v[26:29]
	v_mfma_f32_16x16x32_bf16 v[14:17], v[134:137], v[212:215], v[14:17]
	v_mfma_f32_16x16x32_bf16 v[10:13], v[142:145], v[212:215], v[10:13]
	s_setprio 0
	s_setprio 1
	v_mfma_f32_16x16x32_bf16 v[54:57], v[146:149], v[162:165], 0
	v_mfma_f32_16x16x32_bf16 v[50:53], v[154:157], v[162:165], 0
	v_mfma_f32_16x16x32_bf16 v[38:41], v[146:149], v[170:173], 0
	v_mfma_f32_16x16x32_bf16 v[34:37], v[154:157], v[170:173], 0
	v_mfma_f32_16x16x32_bf16 v[22:25], v[146:149], v[194:197], 0
	v_mfma_f32_16x16x32_bf16 v[18:21], v[154:157], v[194:197], 0
	v_mfma_f32_16x16x32_bf16 v[6:9], v[146:149], v[202:205], 0
	v_mfma_f32_16x16x32_bf16 v[2:5], v[154:157], v[202:205], 0
	v_mfma_f32_16x16x32_bf16 v[54:57], v[150:153], v[166:169], v[54:57]
	v_mfma_f32_16x16x32_bf16 v[50:53], v[158:161], v[166:169], v[50:53]
	v_mfma_f32_16x16x32_bf16 v[38:41], v[150:153], v[174:177], v[38:41]
	v_mfma_f32_16x16x32_bf16 v[34:37], v[158:161], v[174:177], v[34:37]
	v_mfma_f32_16x16x32_bf16 v[22:25], v[150:153], v[198:201], v[22:25]
	v_mfma_f32_16x16x32_bf16 v[18:21], v[158:161], v[198:201], v[18:21]
	v_mfma_f32_16x16x32_bf16 v[6:9], v[150:153], v[212:215], v[6:9]
	v_mfma_f32_16x16x32_bf16 v[2:5], v[158:161], v[212:215], v[2:5]
	s_setprio 0
	s_barrier
	s_add_i32 s56, 0, 0x18000
	s_add_i32 s57, 0, 0x1c000
	ds_read_b128 v[130:133], v254
	ds_read_b128 v[134:137], v254 offset:1024
	ds_read_b128 v[138:141], v254 offset:2048
	ds_read_b128 v[142:145], v254 offset:3072
	ds_read_b128 v[146:149], v255
	ds_read_b128 v[150:153], v255 offset:1024
	ds_read_b128 v[154:157], v255 offset:2048
	ds_read_b128 v[158:161], v255 offset:3072
	s_add_u32 s34, s34, 0x40000
	s_addc_u32 s35, s35, 0
	s_mov_b32 m0, s41
	v_lshl_add_u64 v[224:225], s[34:35], 0, v[182:183]
	ds_read_b128 v[162:165], v211 offset:32768
	ds_read_b128 v[166:169], v211 offset:33792
	ds_read_b128 v[170:173], v211 offset:34816
	ds_read_b128 v[174:177], v211 offset:35840
	ds_read_b128 v[194:197], v211 offset:36864
	ds_read_b128 v[198:201], v211 offset:37888
	ds_read_b128 v[202:205], v211 offset:38912
	ds_read_b128 v[212:215], v211 offset:39936
	global_load_lds_dwordx4 v[224:225], off
	v_lshl_add_u64 v[224:225], s[34:35], 0, v[186:187]
	s_mov_b32 m0, s42
	s_nop 0
	global_load_lds_dwordx4 v[224:225], off
	s_waitcnt vmcnt(8)
	s_waitcnt lgkmcnt(0)
	s_barrier
	s_setprio 1
	s_waitcnt lgkmcnt(0)
	v_mfma_f32_16x16x32_bf16 v[126:129], v[130:133], v[162:165], v[126:129]
	v_mfma_f32_16x16x32_bf16 v[122:125], v[138:141], v[162:165], v[122:125]
	v_mfma_f32_16x16x32_bf16 v[110:113], v[130:133], v[170:173], v[110:113]
	v_mfma_f32_16x16x32_bf16 v[106:109], v[138:141], v[170:173], v[106:109]
	v_mfma_f32_16x16x32_bf16 v[94:97], v[130:133], v[194:197], v[94:97]
	v_mfma_f32_16x16x32_bf16 v[90:93], v[138:141], v[194:197], v[90:93]
	v_mfma_f32_16x16x32_bf16 v[78:81], v[130:133], v[202:205], v[78:81]
	v_mfma_f32_16x16x32_bf16 v[74:77], v[138:141], v[202:205], v[74:77]
	v_mfma_f32_16x16x32_bf16 v[126:129], v[134:137], v[166:169], v[126:129]
	v_mfma_f32_16x16x32_bf16 v[122:125], v[142:145], v[166:169], v[122:125]
	v_mfma_f32_16x16x32_bf16 v[110:113], v[134:137], v[174:177], v[110:113]
	v_mfma_f32_16x16x32_bf16 v[106:109], v[142:145], v[174:177], v[106:109]
	v_mfma_f32_16x16x32_bf16 v[94:97], v[134:137], v[198:201], v[94:97]
	v_mfma_f32_16x16x32_bf16 v[90:93], v[142:145], v[198:201], v[90:93]
	v_mfma_f32_16x16x32_bf16 v[78:81], v[134:137], v[212:215], v[78:81]
	v_mfma_f32_16x16x32_bf16 v[74:77], v[142:145], v[212:215], v[74:77]
	s_setprio 0
	s_setprio 1
	v_mfma_f32_16x16x32_bf16 v[118:121], v[146:149], v[162:165], v[118:121]
	v_mfma_f32_16x16x32_bf16 v[114:117], v[154:157], v[162:165], v[114:117]
	v_mfma_f32_16x16x32_bf16 v[102:105], v[146:149], v[170:173], v[102:105]
	v_mfma_f32_16x16x32_bf16 v[98:101], v[154:157], v[170:173], v[98:101]
	v_mfma_f32_16x16x32_bf16 v[86:89], v[146:149], v[194:197], v[86:89]
	v_mfma_f32_16x16x32_bf16 v[82:85], v[154:157], v[194:197], v[82:85]
	v_mfma_f32_16x16x32_bf16 v[70:73], v[146:149], v[202:205], v[70:73]
	v_mfma_f32_16x16x32_bf16 v[66:69], v[154:157], v[202:205], v[66:69]
	v_mfma_f32_16x16x32_bf16 v[118:121], v[150:153], v[166:169], v[118:121]
	v_mfma_f32_16x16x32_bf16 v[114:117], v[158:161], v[166:169], v[114:117]
	v_mfma_f32_16x16x32_bf16 v[102:105], v[150:153], v[174:177], v[102:105]
	v_mfma_f32_16x16x32_bf16 v[98:101], v[158:161], v[174:177], v[98:101]
	v_mfma_f32_16x16x32_bf16 v[86:89], v[150:153], v[198:201], v[86:89]
	v_mfma_f32_16x16x32_bf16 v[82:85], v[158:161], v[198:201], v[82:85]
	v_mfma_f32_16x16x32_bf16 v[70:73], v[150:153], v[212:215], v[70:73]
	v_mfma_f32_16x16x32_bf16 v[66:69], v[158:161], v[212:215], v[66:69]
	s_setprio 0
	s_barrier
	s_add_i32 s34, s56, s38
	v_lshl_add_u64 v[216:217], v[216:217], 0, s[22:23]
	s_mov_b32 m0, s34
	ds_read_b128 v[162:165], v211 offset:49152
	ds_read_b128 v[166:169], v211 offset:50176
	ds_read_b128 v[170:173], v211 offset:51200
	ds_read_b128 v[174:177], v211 offset:52224
	ds_read_b128 v[194:197], v211 offset:53248
	ds_read_b128 v[198:201], v211 offset:54272
	ds_read_b128 v[202:205], v211 offset:55296
	ds_read_b128 v[212:215], v211 offset:56320
	global_load_lds_dwordx4 v[216:217], off
	s_add_i32 m0, s34, 0x2000
	s_add_u32 s30, s30, 0x40080
	v_lshl_add_u64 v[216:217], v[218:219], 0, s[22:23]
	s_addc_u32 s31, s31, 0
	s_add_i32 s34, s57, s38
	global_load_lds_dwordx4 v[216:217], off
	v_lshl_add_u64 v[216:217], s[30:31], 0, v[184:185]
	s_mov_b32 m0, s34
	s_nop 0
	global_load_lds_dwordx4 v[216:217], off
	v_lshl_add_u64 v[216:217], s[30:31], 0, v[188:189]
	s_add_i32 m0, s34, 0x2000
	s_nop 0
	global_load_lds_dwordx4 v[216:217], off
	v_lshl_add_u64 v[216:217], v[220:221], 0, s[22:23]
	s_mov_b32 m0, s44
	s_nop 0
	global_load_lds_dwordx4 v[216:217], off
	v_lshl_add_u64 v[216:217], v[222:223], 0, s[22:23]
	s_mov_b32 m0, s45
	s_nop 0
	global_load_lds_dwordx4 v[216:217], off
	s_waitcnt vmcnt(8)
	s_waitcnt lgkmcnt(0)
	s_barrier
	s_setprio 1
	s_waitcnt lgkmcnt(0)
	v_mfma_f32_16x16x32_bf16 v[62:65], v[130:133], v[162:165], v[62:65]
	v_mfma_f32_16x16x32_bf16 v[58:61], v[138:141], v[162:165], v[58:61]
	v_mfma_f32_16x16x32_bf16 v[46:49], v[130:133], v[170:173], v[46:49]
	v_mfma_f32_16x16x32_bf16 v[42:45], v[138:141], v[170:173], v[42:45]
	v_mfma_f32_16x16x32_bf16 v[30:33], v[130:133], v[194:197], v[30:33]
	v_mfma_f32_16x16x32_bf16 v[26:29], v[138:141], v[194:197], v[26:29]
	v_mfma_f32_16x16x32_bf16 v[14:17], v[130:133], v[202:205], v[14:17]
	v_mfma_f32_16x16x32_bf16 v[10:13], v[138:141], v[202:205], v[10:13]
	v_mfma_f32_16x16x32_bf16 v[62:65], v[134:137], v[166:169], v[62:65]
	v_mfma_f32_16x16x32_bf16 v[58:61], v[142:145], v[166:169], v[58:61]
	v_mfma_f32_16x16x32_bf16 v[46:49], v[134:137], v[174:177], v[46:49]
	v_mfma_f32_16x16x32_bf16 v[42:45], v[142:145], v[174:177], v[42:45]
	v_mfma_f32_16x16x32_bf16 v[30:33], v[134:137], v[198:201], v[30:33]
	v_mfma_f32_16x16x32_bf16 v[26:29], v[142:145], v[198:201], v[26:29]
	v_mfma_f32_16x16x32_bf16 v[14:17], v[134:137], v[212:215], v[14:17]
	v_mfma_f32_16x16x32_bf16 v[10:13], v[142:145], v[212:215], v[10:13]
	s_setprio 0
	s_setprio 1
	v_mfma_f32_16x16x32_bf16 v[54:57], v[146:149], v[162:165], v[54:57]
	v_mfma_f32_16x16x32_bf16 v[50:53], v[154:157], v[162:165], v[50:53]
	v_mfma_f32_16x16x32_bf16 v[38:41], v[146:149], v[170:173], v[38:41]
	v_mfma_f32_16x16x32_bf16 v[34:37], v[154:157], v[170:173], v[34:37]
	v_mfma_f32_16x16x32_bf16 v[22:25], v[146:149], v[194:197], v[22:25]
	v_mfma_f32_16x16x32_bf16 v[18:21], v[154:157], v[194:197], v[18:21]
	v_mfma_f32_16x16x32_bf16 v[6:9], v[146:149], v[202:205], v[6:9]
	v_mfma_f32_16x16x32_bf16 v[2:5], v[154:157], v[202:205], v[2:5]
	v_mfma_f32_16x16x32_bf16 v[54:57], v[150:153], v[166:169], v[54:57]
	v_mfma_f32_16x16x32_bf16 v[50:53], v[158:161], v[166:169], v[50:53]
	v_mfma_f32_16x16x32_bf16 v[38:41], v[150:153], v[174:177], v[38:41]
	v_mfma_f32_16x16x32_bf16 v[34:37], v[158:161], v[174:177], v[34:37]
	v_mfma_f32_16x16x32_bf16 v[22:25], v[150:153], v[198:201], v[22:25]
	v_mfma_f32_16x16x32_bf16 v[18:21], v[158:161], v[198:201], v[18:21]
	v_mfma_f32_16x16x32_bf16 v[6:9], v[150:153], v[212:215], v[6:9]
	v_mfma_f32_16x16x32_bf16 v[2:5], v[158:161], v[212:215], v[2:5]
	s_setprio 0
	s_barrier
	s_add_i32 s55, s55, 2
	s_add_u32 s28, s28, 0x100
	s_addc_u32 s29, s29, 0
	s_add_u32 s53, s53, 0x100
	s_addc_u32 s54, s54, 0
	s_cmp_gt_u32 s55, 13
	s_cbranch_scc1 .Lpeel_x3
.LBB0_903:
	ds_read_b128 v[130:133], v209
	ds_read_b128 v[134:137], v209 offset:1024
	ds_read_b128 v[138:141], v209 offset:2048
	ds_read_b128 v[142:145], v209 offset:3072
	ds_read_b128 v[146:149], v210
	ds_read_b128 v[150:153], v210 offset:1024
	ds_read_b128 v[154:157], v210 offset:2048
	ds_read_b128 v[158:161], v210 offset:3072
	s_add_u32 s30, s28, 0xfffc0080
	s_addc_u32 s31, s29, -1
	s_cmp_eq_u32 s55, 12
	s_cselect_b32 s35, s1, s31
	s_cselect_b32 s34, s50, s30
	s_cselect_b32 s31, s51, s54
	s_cselect_b32 s30, s52, s53
	v_lshl_add_u64 v[216:217], s[28:29], 0, v[190:191]
	s_add_i32 m0, s39, 0xc000
	ds_read_b128 v[162:165], v211
	ds_read_b128 v[166:169], v211 offset:1024
	ds_read_b128 v[170:173], v211 offset:2048
	ds_read_b128 v[174:177], v211 offset:3072
	ds_read_b128 v[194:197], v211 offset:4096
	ds_read_b128 v[198:201], v211 offset:5120
	ds_read_b128 v[202:205], v211 offset:6144
	ds_read_b128 v[212:215], v211 offset:7168
	global_load_lds_dwordx4 v[216:217], off
	v_lshl_add_u64 v[216:217], s[28:29], 0, v[192:193]
	s_add_i32 m0, s39, 0xe000
	s_nop 0
	global_load_lds_dwordx4 v[216:217], off
	s_waitcnt vmcnt(8)
	s_waitcnt lgkmcnt(0)
	s_barrier
	s_setprio 1
	s_waitcnt lgkmcnt(0)
	v_mfma_f32_16x16x32_bf16 v[126:129], v[130:133], v[162:165], v[126:129]
	v_mfma_f32_16x16x32_bf16 v[122:125], v[138:141], v[162:165], v[122:125]
	v_mfma_f32_16x16x32_bf16 v[110:113], v[130:133], v[170:173], v[110:113]
	v_mfma_f32_16x16x32_bf16 v[106:109], v[138:141], v[170:173], v[106:109]
	v_mfma_f32_16x16x32_bf16 v[94:97], v[130:133], v[194:197], v[94:97]
	v_mfma_f32_16x16x32_bf16 v[90:93], v[138:141], v[194:197], v[90:93]
	v_mfma_f32_16x16x32_bf16 v[78:81], v[130:133], v[202:205], v[78:81]
	v_mfma_f32_16x16x32_bf16 v[74:77], v[138:141], v[202:205], v[74:77]
	v_mfma_f32_16x16x32_bf16 v[126:129], v[134:137], v[166:169], v[126:129]
	v_mfma_f32_16x16x32_bf16 v[122:125], v[142:145], v[166:169], v[122:125]
	v_mfma_f32_16x16x32_bf16 v[110:113], v[134:137], v[174:177], v[110:113]
	v_mfma_f32_16x16x32_bf16 v[106:109], v[142:145], v[174:177], v[106:109]
	v_mfma_f32_16x16x32_bf16 v[94:97], v[134:137], v[198:201], v[94:97]
	v_mfma_f32_16x16x32_bf16 v[90:93], v[142:145], v[198:201], v[90:93]
	v_mfma_f32_16x16x32_bf16 v[78:81], v[134:137], v[212:215], v[78:81]
	v_mfma_f32_16x16x32_bf16 v[74:77], v[142:145], v[212:215], v[74:77]
	s_setprio 0
	s_setprio 1
	v_mfma_f32_16x16x32_bf16 v[118:121], v[146:149], v[162:165], v[118:121]
	v_mfma_f32_16x16x32_bf16 v[114:117], v[154:157], v[162:165], v[114:117]
	v_mfma_f32_16x16x32_bf16 v[102:105], v[146:149], v[170:173], v[102:105]
	v_mfma_f32_16x16x32_bf16 v[98:101], v[154:157], v[170:173], v[98:101]
	v_mfma_f32_16x16x32_bf16 v[86:89], v[146:149], v[194:197], v[86:89]
	v_mfma_f32_16x16x32_bf16 v[82:85], v[154:157], v[194:197], v[82:85]
	v_mfma_f32_16x16x32_bf16 v[70:73], v[146:149], v[202:205], v[70:73]
	v_mfma_f32_16x16x32_bf16 v[66:69], v[154:157], v[202:205], v[66:69]
	v_mfma_f32_16x16x32_bf16 v[118:121], v[150:153], v[166:169], v[118:121]
	v_mfma_f32_16x16x32_bf16 v[114:117], v[158:161], v[166:169], v[114:117]
	v_mfma_f32_16x16x32_bf16 v[102:105], v[150:153], v[174:177], v[102:105]
	v_mfma_f32_16x16x32_bf16 v[98:101], v[158:161], v[174:177], v[98:101]
	v_mfma_f32_16x16x32_bf16 v[86:89], v[150:153], v[198:201], v[86:89]
	v_mfma_f32_16x16x32_bf16 v[82:85], v[158:161], v[198:201], v[82:85]
	v_mfma_f32_16x16x32_bf16 v[70:73], v[150:153], v[212:215], v[70:73]
	v_mfma_f32_16x16x32_bf16 v[66:69], v[158:161], v[212:215], v[66:69]
	s_setprio 0
	s_barrier
	s_add_i32 s56, s48, s38
	v_lshl_add_u64 v[216:217], s[30:31], 0, v[184:185]
	s_mov_b32 m0, s56
	ds_read_b128 v[162:165], v211 offset:16384
	ds_read_b128 v[166:169], v211 offset:17408
	ds_read_b128 v[170:173], v211 offset:18432
	ds_read_b128 v[174:177], v211 offset:19456
	ds_read_b128 v[194:197], v211 offset:20480
	ds_read_b128 v[198:201], v211 offset:21504
	ds_read_b128 v[202:205], v211 offset:22528
	ds_read_b128 v[212:215], v211 offset:23552
	global_load_lds_dwordx4 v[216:217], off
	s_add_i32 m0, s56, 0x2000
	s_add_u32 s56, s30, 0x40000
	v_lshl_add_u64 v[218:219], s[30:31], 0, v[188:189]
	s_addc_u32 s57, s31, 0
	s_add_i32 s58, s49, s38
	global_load_lds_dwordx4 v[218:219], off
	v_lshl_add_u64 v[220:221], s[56:57], 0, v[184:185]
	s_mov_b32 m0, s58
	v_lshl_add_u64 v[222:223], s[34:35], 0, v[186:187]
	global_load_lds_dwordx4 v[220:221], off
	v_lshl_add_u64 v[220:221], s[56:57], 0, v[188:189]
	s_add_i32 m0, s58, 0x2000
	s_nop 0
	global_load_lds_dwordx4 v[220:221], off
	v_lshl_add_u64 v[220:221], s[34:35], 0, v[182:183]
	s_mov_b32 m0, s39
	s_nop 0
	global_load_lds_dwordx4 v[220:221], off
	s_mov_b32 m0, s40
	s_nop 0
	global_load_lds_dwordx4 v[222:223], off
	s_waitcnt vmcnt(8)
	s_waitcnt lgkmcnt(0)
	s_barrier
	s_setprio 1
	s_waitcnt lgkmcnt(0)
	v_mfma_f32_16x16x32_bf16 v[62:65], v[130:133], v[162:165], v[62:65]
	v_mfma_f32_16x16x32_bf16 v[58:61], v[138:141], v[162:165], v[58:61]
	v_mfma_f32_16x16x32_bf16 v[46:49], v[130:133], v[170:173], v[46:49]
	v_mfma_f32_16x16x32_bf16 v[42:45], v[138:141], v[170:173], v[42:45]
	v_mfma_f32_16x16x32_bf16 v[30:33], v[130:133], v[194:197], v[30:33]
	v_mfma_f32_16x16x32_bf16 v[26:29], v[138:141], v[194:197], v[26:29]
	v_mfma_f32_16x16x32_bf16 v[14:17], v[130:133], v[202:205], v[14:17]
	v_mfma_f32_16x16x32_bf16 v[10:13], v[138:141], v[202:205], v[10:13]
	v_mfma_f32_16x16x32_bf16 v[62:65], v[134:137], v[166:169], v[62:65]
	v_mfma_f32_16x16x32_bf16 v[58:61], v[142:145], v[166:169], v[58:61]
	v_mfma_f32_16x16x32_bf16 v[46:49], v[134:137], v[174:177], v[46:49]
	v_mfma_f32_16x16x32_bf16 v[42:45], v[142:145], v[174:177], v[42:45]
	v_mfma_f32_16x16x32_bf16 v[30:33], v[134:137], v[198:201], v[30:33]
	v_mfma_f32_16x16x32_bf16 v[26:29], v[142:145], v[198:201], v[26:29]
	v_mfma_f32_16x16x32_bf16 v[14:17], v[134:137], v[212:215], v[14:17]
	v_mfma_f32_16x16x32_bf16 v[10:13], v[142:145], v[212:215], v[10:13]
	s_setprio 0
	s_setprio 1
	v_mfma_f32_16x16x32_bf16 v[54:57], v[146:149], v[162:165], v[54:57]
	v_mfma_f32_16x16x32_bf16 v[50:53], v[154:157], v[162:165], v[50:53]
	v_mfma_f32_16x16x32_bf16 v[38:41], v[146:149], v[170:173], v[38:41]
	v_mfma_f32_16x16x32_bf16 v[34:37], v[154:157], v[170:173], v[34:37]
	v_mfma_f32_16x16x32_bf16 v[22:25], v[146:149], v[194:197], v[22:25]
	v_mfma_f32_16x16x32_bf16 v[18:21], v[154:157], v[194:197], v[18:21]
	v_mfma_f32_16x16x32_bf16 v[6:9], v[146:149], v[202:205], v[6:9]
	v_mfma_f32_16x16x32_bf16 v[2:5], v[154:157], v[202:205], v[2:5]
	v_mfma_f32_16x16x32_bf16 v[54:57], v[150:153], v[166:169], v[54:57]
	v_mfma_f32_16x16x32_bf16 v[50:53], v[158:161], v[166:169], v[50:53]
	v_mfma_f32_16x16x32_bf16 v[38:41], v[150:153], v[174:177], v[38:41]
	v_mfma_f32_16x16x32_bf16 v[34:37], v[158:161], v[174:177], v[34:37]
	v_mfma_f32_16x16x32_bf16 v[22:25], v[150:153], v[198:201], v[22:25]
	v_mfma_f32_16x16x32_bf16 v[18:21], v[158:161], v[198:201], v[18:21]
	v_mfma_f32_16x16x32_bf16 v[6:9], v[150:153], v[212:215], v[6:9]
	v_mfma_f32_16x16x32_bf16 v[2:5], v[158:161], v[212:215], v[2:5]
	s_setprio 0
	s_barrier
	s_add_i32 s56, 0, 0x18000
	s_add_i32 s57, 0, 0x1c000
	ds_read_b128 v[130:133], v254
	ds_read_b128 v[134:137], v254 offset:1024
	ds_read_b128 v[138:141], v254 offset:2048
	ds_read_b128 v[142:145], v254 offset:3072
	ds_read_b128 v[146:149], v255
	ds_read_b128 v[150:153], v255 offset:1024
	ds_read_b128 v[154:157], v255 offset:2048
	ds_read_b128 v[158:161], v255 offset:3072
	s_add_u32 s34, s34, 0x40000
	s_addc_u32 s35, s35, 0
	s_mov_b32 m0, s41
	v_lshl_add_u64 v[224:225], s[34:35], 0, v[182:183]
	ds_read_b128 v[162:165], v211 offset:32768
	ds_read_b128 v[166:169], v211 offset:33792
	ds_read_b128 v[170:173], v211 offset:34816
	ds_read_b128 v[174:177], v211 offset:35840
	ds_read_b128 v[194:197], v211 offset:36864
	ds_read_b128 v[198:201], v211 offset:37888
	ds_read_b128 v[202:205], v211 offset:38912
	ds_read_b128 v[212:215], v211 offset:39936
	global_load_lds_dwordx4 v[224:225], off
	v_lshl_add_u64 v[224:225], s[34:35], 0, v[186:187]
	s_mov_b32 m0, s42
	s_nop 0
	global_load_lds_dwordx4 v[224:225], off
	s_waitcnt vmcnt(8)
	s_waitcnt lgkmcnt(0)
	s_barrier
	s_setprio 1
	s_waitcnt lgkmcnt(0)
	v_mfma_f32_16x16x32_bf16 v[126:129], v[130:133], v[162:165], v[126:129]
	v_mfma_f32_16x16x32_bf16 v[122:125], v[138:141], v[162:165], v[122:125]
	v_mfma_f32_16x16x32_bf16 v[110:113], v[130:133], v[170:173], v[110:113]
	v_mfma_f32_16x16x32_bf16 v[106:109], v[138:141], v[170:173], v[106:109]
	v_mfma_f32_16x16x32_bf16 v[94:97], v[130:133], v[194:197], v[94:97]
	v_mfma_f32_16x16x32_bf16 v[90:93], v[138:141], v[194:197], v[90:93]
	v_mfma_f32_16x16x32_bf16 v[78:81], v[130:133], v[202:205], v[78:81]
	v_mfma_f32_16x16x32_bf16 v[74:77], v[138:141], v[202:205], v[74:77]
	v_mfma_f32_16x16x32_bf16 v[126:129], v[134:137], v[166:169], v[126:129]
	v_mfma_f32_16x16x32_bf16 v[122:125], v[142:145], v[166:169], v[122:125]
	v_mfma_f32_16x16x32_bf16 v[110:113], v[134:137], v[174:177], v[110:113]
	v_mfma_f32_16x16x32_bf16 v[106:109], v[142:145], v[174:177], v[106:109]
	v_mfma_f32_16x16x32_bf16 v[94:97], v[134:137], v[198:201], v[94:97]
	v_mfma_f32_16x16x32_bf16 v[90:93], v[142:145], v[198:201], v[90:93]
	v_mfma_f32_16x16x32_bf16 v[78:81], v[134:137], v[212:215], v[78:81]
	v_mfma_f32_16x16x32_bf16 v[74:77], v[142:145], v[212:215], v[74:77]
	s_setprio 0
	s_setprio 1
	v_mfma_f32_16x16x32_bf16 v[118:121], v[146:149], v[162:165], v[118:121]
	v_mfma_f32_16x16x32_bf16 v[114:117], v[154:157], v[162:165], v[114:117]
	v_mfma_f32_16x16x32_bf16 v[102:105], v[146:149], v[170:173], v[102:105]
	v_mfma_f32_16x16x32_bf16 v[98:101], v[154:157], v[170:173], v[98:101]
	v_mfma_f32_16x16x32_bf16 v[86:89], v[146:149], v[194:197], v[86:89]
	v_mfma_f32_16x16x32_bf16 v[82:85], v[154:157], v[194:197], v[82:85]
	v_mfma_f32_16x16x32_bf16 v[70:73], v[146:149], v[202:205], v[70:73]
	v_mfma_f32_16x16x32_bf16 v[66:69], v[154:157], v[202:205], v[66:69]
	v_mfma_f32_16x16x32_bf16 v[118:121], v[150:153], v[166:169], v[118:121]
	v_mfma_f32_16x16x32_bf16 v[114:117], v[158:161], v[166:169], v[114:117]
	v_mfma_f32_16x16x32_bf16 v[102:105], v[150:153], v[174:177], v[102:105]
	v_mfma_f32_16x16x32_bf16 v[98:101], v[158:161], v[174:177], v[98:101]
	v_mfma_f32_16x16x32_bf16 v[86:89], v[150:153], v[198:201], v[86:89]
	v_mfma_f32_16x16x32_bf16 v[82:85], v[158:161], v[198:201], v[82:85]
	v_mfma_f32_16x16x32_bf16 v[70:73], v[150:153], v[212:215], v[70:73]
	v_mfma_f32_16x16x32_bf16 v[66:69], v[158:161], v[212:215], v[66:69]
	s_setprio 0
	s_barrier
	s_add_i32 s34, s56, s38
	v_lshl_add_u64 v[216:217], v[216:217], 0, s[22:23]
	s_mov_b32 m0, s34
	ds_read_b128 v[162:165], v211 offset:49152
	ds_read_b128 v[166:169], v211 offset:50176
	ds_read_b128 v[170:173], v211 offset:51200
	ds_read_b128 v[174:177], v211 offset:52224
	ds_read_b128 v[194:197], v211 offset:53248
	ds_read_b128 v[198:201], v211 offset:54272
	ds_read_b128 v[202:205], v211 offset:55296
	ds_read_b128 v[212:215], v211 offset:56320
	global_load_lds_dwordx4 v[216:217], off
	s_add_i32 m0, s34, 0x2000
	s_add_u32 s30, s30, 0x40080
	v_lshl_add_u64 v[216:217], v[218:219], 0, s[22:23]
	s_addc_u32 s31, s31, 0
	s_add_i32 s34, s57, s38
	global_load_lds_dwordx4 v[216:217], off
	v_lshl_add_u64 v[216:217], s[30:31], 0, v[184:185]
	s_mov_b32 m0, s34
	s_nop 0
	global_load_lds_dwordx4 v[216:217], off
	v_lshl_add_u64 v[216:217], s[30:31], 0, v[188:189]
	s_add_i32 m0, s34, 0x2000
	s_nop 0
	global_load_lds_dwordx4 v[216:217], off
	v_lshl_add_u64 v[216:217], v[220:221], 0, s[22:23]
	s_mov_b32 m0, s44
	s_nop 0
	global_load_lds_dwordx4 v[216:217], off
	v_lshl_add_u64 v[216:217], v[222:223], 0, s[22:23]
	s_mov_b32 m0, s45
	s_nop 0
	global_load_lds_dwordx4 v[216:217], off
	s_waitcnt vmcnt(8)
	s_waitcnt lgkmcnt(0)
	s_barrier
	s_setprio 1
	s_waitcnt lgkmcnt(0)
	v_mfma_f32_16x16x32_bf16 v[62:65], v[130:133], v[162:165], v[62:65]
	v_mfma_f32_16x16x32_bf16 v[58:61], v[138:141], v[162:165], v[58:61]
	v_mfma_f32_16x16x32_bf16 v[46:49], v[130:133], v[170:173], v[46:49]
	v_mfma_f32_16x16x32_bf16 v[42:45], v[138:141], v[170:173], v[42:45]
	v_mfma_f32_16x16x32_bf16 v[30:33], v[130:133], v[194:197], v[30:33]
	v_mfma_f32_16x16x32_bf16 v[26:29], v[138:141], v[194:197], v[26:29]
	v_mfma_f32_16x16x32_bf16 v[14:17], v[130:133], v[202:205], v[14:17]
	v_mfma_f32_16x16x32_bf16 v[10:13], v[138:141], v[202:205], v[10:13]
	v_mfma_f32_16x16x32_bf16 v[62:65], v[134:137], v[166:169], v[62:65]
	v_mfma_f32_16x16x32_bf16 v[58:61], v[142:145], v[166:169], v[58:61]
	v_mfma_f32_16x16x32_bf16 v[46:49], v[134:137], v[174:177], v[46:49]
	v_mfma_f32_16x16x32_bf16 v[42:45], v[142:145], v[174:177], v[42:45]
	v_mfma_f32_16x16x32_bf16 v[30:33], v[134:137], v[198:201], v[30:33]
	v_mfma_f32_16x16x32_bf16 v[26:29], v[142:145], v[198:201], v[26:29]
	v_mfma_f32_16x16x32_bf16 v[14:17], v[134:137], v[212:215], v[14:17]
	v_mfma_f32_16x16x32_bf16 v[10:13], v[142:145], v[212:215], v[10:13]
	s_setprio 0
	s_setprio 1
	v_mfma_f32_16x16x32_bf16 v[54:57], v[146:149], v[162:165], v[54:57]
	v_mfma_f32_16x16x32_bf16 v[50:53], v[154:157], v[162:165], v[50:53]
	v_mfma_f32_16x16x32_bf16 v[38:41], v[146:149], v[170:173], v[38:41]
	v_mfma_f32_16x16x32_bf16 v[34:37], v[154:157], v[170:173], v[34:37]
	v_mfma_f32_16x16x32_bf16 v[22:25], v[146:149], v[194:197], v[22:25]
	v_mfma_f32_16x16x32_bf16 v[18:21], v[154:157], v[194:197], v[18:21]
	v_mfma_f32_16x16x32_bf16 v[6:9], v[146:149], v[202:205], v[6:9]
	v_mfma_f32_16x16x32_bf16 v[2:5], v[154:157], v[202:205], v[2:5]
	v_mfma_f32_16x16x32_bf16 v[54:57], v[150:153], v[166:169], v[54:57]
	v_mfma_f32_16x16x32_bf16 v[50:53], v[158:161], v[166:169], v[50:53]
	v_mfma_f32_16x16x32_bf16 v[38:41], v[150:153], v[174:177], v[38:41]
	v_mfma_f32_16x16x32_bf16 v[34:37], v[158:161], v[174:177], v[34:37]
	v_mfma_f32_16x16x32_bf16 v[22:25], v[150:153], v[198:201], v[22:25]
	v_mfma_f32_16x16x32_bf16 v[18:21], v[158:161], v[198:201], v[18:21]
	v_mfma_f32_16x16x32_bf16 v[6:9], v[150:153], v[212:215], v[6:9]
	v_mfma_f32_16x16x32_bf16 v[2:5], v[158:161], v[212:215], v[2:5]
	s_setprio 0
	s_barrier
	s_add_i32 s55, s55, 2
	s_add_u32 s28, s28, 0x100
	s_addc_u32 s29, s29, 0
	s_add_u32 s53, s53, 0x100
	s_addc_u32 s54, s54, 0
	s_cmp_gt_u32 s55, 13
	s_cbranch_scc0 .LBB0_903

.LBB0_990:
	s_ashr_i32 s37, s36, 31
	s_lshl_b64 s[2:3], s[36:37], 19
	s_add_u32 s40, s48, s2
	s_addc_u32 s41, s49, s3
	s_and_b64 s[2:3], s[44:45], exec
	s_cselect_b32 s1, s41, s9
	s_cselect_b32 s2, s40, s8
	s_ashr_i32 s39, s38, 31
	s_lshl_b64 s[4:5], s[38:39], 19
	s_add_u32 s42, s50, s4
	s_addc_u32 s43, s51, s5
	s_and_b64 s[4:5], s[44:45], exec
	s_cselect_b32 s3, s43, s11
	s_cselect_b32 s4, s42, s10
	s_add_u32 s8, s8, 0x40080
	s_addc_u32 s9, s9, 0
	s_add_u32 s5, s10, 0x100
	s_addc_u32 s7, s11, 0
	s_mov_b32 s22, -2
	v_add_u32_e32 v254, 0x18000, v213
	v_add_u32_e32 v255, 0x1c000, v213
	ds_read_b128 v[66:69], v219
	ds_read_b128 v[70:73], v219 offset:1024
	ds_read_b128 v[86:89], v219 offset:2048
	ds_read_b128 v[106:109], v219 offset:3072
	ds_read_b128 v[146:149], v220
	ds_read_b128 v[150:153], v220 offset:1024
	ds_read_b128 v[154:157], v220 offset:2048
	ds_read_b128 v[158:161], v220 offset:3072
	s_add_u32 s10, s8, 0xfffc0080
	s_addc_u32 s11, s9, -1
	s_cmp_eq_u32 s22, 12
	s_cselect_b32 s45, s1, s11
	s_cselect_b32 s44, s2, s10
	s_cselect_b32 s11, s3, s7
	s_cselect_b32 s10, s4, s5
	s_add_i32 m0, s54, 0xc000
	ds_read_b128 v[162:165], v221
	ds_read_b128 v[166:169], v221 offset:1024
	ds_read_b128 v[170:173], v221 offset:2048
	ds_read_b128 v[174:177], v221 offset:3072
	ds_read_b128 v[196:199], v221 offset:4096
	ds_read_b128 v[200:203], v221 offset:5120
	ds_read_b128 v[204:207], v221 offset:6144
	ds_read_b128 v[208:211], v221 offset:7168
	global_load_lds_dwordx4 v192, s[8:9]
	s_add_i32 m0, s54, 0xe000
	s_nop 0
	global_load_lds_dwordx4 v194, s[8:9]
	s_waitcnt vmcnt(8)
	s_waitcnt lgkmcnt(0)
	s_barrier
	s_setprio 1
	s_waitcnt lgkmcnt(0)
	v_mfma_f32_16x16x32_bf16 v[142:145], v[66:69], v[162:165], 0
	v_mfma_f32_16x16x32_bf16 v[134:137], v[86:89], v[162:165], 0
	v_mfma_f32_16x16x32_bf16 v[126:129], v[66:69], v[170:173], 0
	v_mfma_f32_16x16x32_bf16 v[122:125], v[86:89], v[170:173], 0
	v_mfma_f32_16x16x32_bf16 v[110:113], v[66:69], v[196:199], 0
	v_mfma_f32_16x16x32_bf16 v[102:105], v[86:89], v[196:199], 0
	v_mfma_f32_16x16x32_bf16 v[90:93], v[66:69], v[204:207], 0
	v_mfma_f32_16x16x32_bf16 v[82:85], v[86:89], v[204:207], 0
	v_mfma_f32_16x16x32_bf16 v[142:145], v[70:73], v[166:169], v[142:145]
	v_mfma_f32_16x16x32_bf16 v[134:137], v[106:109], v[166:169], v[134:137]
	v_mfma_f32_16x16x32_bf16 v[126:129], v[70:73], v[174:177], v[126:129]
	v_mfma_f32_16x16x32_bf16 v[122:125], v[106:109], v[174:177], v[122:125]
	v_mfma_f32_16x16x32_bf16 v[110:113], v[70:73], v[200:203], v[110:113]
	v_mfma_f32_16x16x32_bf16 v[102:105], v[106:109], v[200:203], v[102:105]
	v_mfma_f32_16x16x32_bf16 v[90:93], v[70:73], v[208:211], v[90:93]
	v_mfma_f32_16x16x32_bf16 v[82:85], v[106:109], v[208:211], v[82:85]
	s_setprio 0
	s_setprio 1
	v_mfma_f32_16x16x32_bf16 v[138:141], v[146:149], v[162:165], 0
	v_mfma_f32_16x16x32_bf16 v[130:133], v[154:157], v[162:165], 0
	v_mfma_f32_16x16x32_bf16 v[118:121], v[146:149], v[170:173], 0
	v_mfma_f32_16x16x32_bf16 v[114:117], v[154:157], v[170:173], 0
	v_mfma_f32_16x16x32_bf16 v[98:101], v[146:149], v[196:199], 0
	v_mfma_f32_16x16x32_bf16 v[94:97], v[154:157], v[196:199], 0
	v_mfma_f32_16x16x32_bf16 v[78:81], v[146:149], v[204:207], 0
	v_mfma_f32_16x16x32_bf16 v[74:77], v[154:157], v[204:207], 0
	v_mfma_f32_16x16x32_bf16 v[138:141], v[150:153], v[166:169], v[138:141]
	v_mfma_f32_16x16x32_bf16 v[130:133], v[158:161], v[166:169], v[130:133]
	v_mfma_f32_16x16x32_bf16 v[118:121], v[150:153], v[174:177], v[118:121]
	v_mfma_f32_16x16x32_bf16 v[114:117], v[158:161], v[174:177], v[114:117]
	v_mfma_f32_16x16x32_bf16 v[98:101], v[150:153], v[200:203], v[98:101]
	v_mfma_f32_16x16x32_bf16 v[94:97], v[158:161], v[200:203], v[94:97]
	v_mfma_f32_16x16x32_bf16 v[78:81], v[150:153], v[208:211], v[78:81]
	v_mfma_f32_16x16x32_bf16 v[74:77], v[158:161], v[208:211], v[74:77]
	s_setprio 0
	s_barrier
	s_add_i32 s37, s62, s53
	s_mov_b32 m0, s37
	ds_read_b128 v[162:165], v221 offset:16384
	ds_read_b128 v[166:169], v221 offset:17408
	ds_read_b128 v[170:173], v221 offset:18432
	ds_read_b128 v[174:177], v221 offset:19456
	ds_read_b128 v[196:199], v221 offset:20480
	ds_read_b128 v[200:203], v221 offset:21504
	ds_read_b128 v[204:207], v221 offset:22528
	ds_read_b128 v[208:211], v221 offset:23552
	global_load_lds_dwordx4 v184, s[10:11]
	s_add_i32 m0, s37, 0x2000
	s_add_u32 s46, s10, 0x40000
	s_addc_u32 s47, s11, 0
	s_add_i32 s37, s63, s53
	global_load_lds_dwordx4 v188, s[10:11]
	s_mov_b32 m0, s37
	s_nop 0
	global_load_lds_dwordx4 v184, s[46:47]
	s_add_i32 m0, s37, 0x2000
	s_nop 0
	global_load_lds_dwordx4 v188, s[46:47]
	s_mov_b32 m0, s54
	s_nop 0
	global_load_lds_dwordx4 v182, s[44:45]
	s_mov_b32 m0, s55
	s_nop 0
	global_load_lds_dwordx4 v186, s[44:45]
	s_waitcnt vmcnt(8)
	s_waitcnt lgkmcnt(0)
	s_barrier
	s_setprio 1
	s_waitcnt lgkmcnt(0)
	v_mfma_f32_16x16x32_bf16 v[62:65], v[66:69], v[162:165], 0
	v_mfma_f32_16x16x32_bf16 v[54:57], v[86:89], v[162:165], 0
	v_mfma_f32_16x16x32_bf16 v[46:49], v[66:69], v[170:173], 0
	v_mfma_f32_16x16x32_bf16 v[42:45], v[86:89], v[170:173], 0
	v_mfma_f32_16x16x32_bf16 v[30:33], v[66:69], v[196:199], 0
	v_mfma_f32_16x16x32_bf16 v[26:29], v[86:89], v[196:199], 0
	v_mfma_f32_16x16x32_bf16 v[14:17], v[66:69], v[204:207], 0
	v_mfma_f32_16x16x32_bf16 v[10:13], v[86:89], v[204:207], 0
	v_mfma_f32_16x16x32_bf16 v[62:65], v[70:73], v[166:169], v[62:65]
	v_mfma_f32_16x16x32_bf16 v[54:57], v[106:109], v[166:169], v[54:57]
	v_mfma_f32_16x16x32_bf16 v[46:49], v[70:73], v[174:177], v[46:49]
	v_mfma_f32_16x16x32_bf16 v[42:45], v[106:109], v[174:177], v[42:45]
	v_mfma_f32_16x16x32_bf16 v[30:33], v[70:73], v[200:203], v[30:33]
	v_mfma_f32_16x16x32_bf16 v[26:29], v[106:109], v[200:203], v[26:29]
	v_mfma_f32_16x16x32_bf16 v[14:17], v[70:73], v[208:211], v[14:17]
	v_mfma_f32_16x16x32_bf16 v[10:13], v[106:109], v[208:211], v[10:13]
	s_setprio 0
	s_setprio 1
	v_mfma_f32_16x16x32_bf16 v[58:61], v[146:149], v[162:165], 0
	v_mfma_f32_16x16x32_bf16 v[50:53], v[154:157], v[162:165], 0
	v_mfma_f32_16x16x32_bf16 v[38:41], v[146:149], v[170:173], 0
	v_mfma_f32_16x16x32_bf16 v[34:37], v[154:157], v[170:173], 0
	v_mfma_f32_16x16x32_bf16 v[22:25], v[146:149], v[196:199], 0
	v_mfma_f32_16x16x32_bf16 v[18:21], v[154:157], v[196:199], 0
	v_mfma_f32_16x16x32_bf16 v[6:9], v[146:149], v[204:207], 0
	v_mfma_f32_16x16x32_bf16 v[2:5], v[154:157], v[204:207], 0
	v_mfma_f32_16x16x32_bf16 v[58:61], v[150:153], v[166:169], v[58:61]
	v_mfma_f32_16x16x32_bf16 v[50:53], v[158:161], v[166:169], v[50:53]
	v_mfma_f32_16x16x32_bf16 v[38:41], v[150:153], v[174:177], v[38:41]
	v_mfma_f32_16x16x32_bf16 v[34:37], v[158:161], v[174:177], v[34:37]
	v_mfma_f32_16x16x32_bf16 v[22:25], v[150:153], v[200:203], v[22:25]
	v_mfma_f32_16x16x32_bf16 v[18:21], v[158:161], v[200:203], v[18:21]
	v_mfma_f32_16x16x32_bf16 v[6:9], v[150:153], v[208:211], v[6:9]
	v_mfma_f32_16x16x32_bf16 v[2:5], v[158:161], v[208:211], v[2:5]
	s_setprio 0
	s_barrier
	s_add_i32 s37, 0, 0x18000
	s_add_i32 s39, 0, 0x1c000
	ds_read_b128 v[66:69], v254
	ds_read_b128 v[70:73], v254 offset:1024
	ds_read_b128 v[86:89], v254 offset:2048
	ds_read_b128 v[106:109], v254 offset:3072
	ds_read_b128 v[146:149], v255
	ds_read_b128 v[150:153], v255 offset:1024
	ds_read_b128 v[154:157], v255 offset:2048
	ds_read_b128 v[158:161], v255 offset:3072
	s_add_u32 s44, s44, 0x40000
	s_addc_u32 s45, s45, 0
	s_mov_b32 m0, s56
	ds_read_b128 v[162:165], v221 offset:32768
	ds_read_b128 v[166:169], v221 offset:33792
	ds_read_b128 v[170:173], v221 offset:34816
	ds_read_b128 v[174:177], v221 offset:35840
	ds_read_b128 v[196:199], v221 offset:36864
	ds_read_b128 v[200:203], v221 offset:37888
	ds_read_b128 v[204:207], v221 offset:38912
	ds_read_b128 v[208:211], v221 offset:39936
	global_load_lds_dwordx4 v182, s[44:45]
	s_mov_b32 m0, s57
	s_nop 0
	global_load_lds_dwordx4 v186, s[44:45]
	s_waitcnt vmcnt(8)
	s_waitcnt lgkmcnt(0)
	s_barrier
	s_setprio 1
	s_waitcnt lgkmcnt(0)
	v_mfma_f32_16x16x32_bf16 v[142:145], v[66:69], v[162:165], v[142:145]
	v_mfma_f32_16x16x32_bf16 v[134:137], v[86:89], v[162:165], v[134:137]
	v_mfma_f32_16x16x32_bf16 v[126:129], v[66:69], v[170:173], v[126:129]
	v_mfma_f32_16x16x32_bf16 v[122:125], v[86:89], v[170:173], v[122:125]
	v_mfma_f32_16x16x32_bf16 v[110:113], v[66:69], v[196:199], v[110:113]
	v_mfma_f32_16x16x32_bf16 v[102:105], v[86:89], v[196:199], v[102:105]
	v_mfma_f32_16x16x32_bf16 v[90:93], v[66:69], v[204:207], v[90:93]
	v_mfma_f32_16x16x32_bf16 v[82:85], v[86:89], v[204:207], v[82:85]
	v_mfma_f32_16x16x32_bf16 v[142:145], v[70:73], v[166:169], v[142:145]
	v_mfma_f32_16x16x32_bf16 v[134:137], v[106:109], v[166:169], v[134:137]
	v_mfma_f32_16x16x32_bf16 v[126:129], v[70:73], v[174:177], v[126:129]
	v_mfma_f32_16x16x32_bf16 v[122:125], v[106:109], v[174:177], v[122:125]
	v_mfma_f32_16x16x32_bf16 v[110:113], v[70:73], v[200:203], v[110:113]
	v_mfma_f32_16x16x32_bf16 v[102:105], v[106:109], v[200:203], v[102:105]
	v_mfma_f32_16x16x32_bf16 v[90:93], v[70:73], v[208:211], v[90:93]
	v_mfma_f32_16x16x32_bf16 v[82:85], v[106:109], v[208:211], v[82:85]
	s_setprio 0
	s_setprio 1
	v_mfma_f32_16x16x32_bf16 v[138:141], v[146:149], v[162:165], v[138:141]
	v_mfma_f32_16x16x32_bf16 v[130:133], v[154:157], v[162:165], v[130:133]
	v_mfma_f32_16x16x32_bf16 v[118:121], v[146:149], v[170:173], v[118:121]
	v_mfma_f32_16x16x32_bf16 v[114:117], v[154:157], v[170:173], v[114:117]
	v_mfma_f32_16x16x32_bf16 v[98:101], v[146:149], v[196:199], v[98:101]
	v_mfma_f32_16x16x32_bf16 v[94:97], v[154:157], v[196:199], v[94:97]
	v_mfma_f32_16x16x32_bf16 v[78:81], v[146:149], v[204:207], v[78:81]
	v_mfma_f32_16x16x32_bf16 v[74:77], v[154:157], v[204:207], v[74:77]
	v_mfma_f32_16x16x32_bf16 v[138:141], v[150:153], v[166:169], v[138:141]
	v_mfma_f32_16x16x32_bf16 v[130:133], v[158:161], v[166:169], v[130:133]
	v_mfma_f32_16x16x32_bf16 v[118:121], v[150:153], v[174:177], v[118:121]
	v_mfma_f32_16x16x32_bf16 v[114:117], v[158:161], v[174:177], v[114:117]
	v_mfma_f32_16x16x32_bf16 v[98:101], v[150:153], v[200:203], v[98:101]
	v_mfma_f32_16x16x32_bf16 v[94:97], v[158:161], v[200:203], v[94:97]
	v_mfma_f32_16x16x32_bf16 v[78:81], v[150:153], v[208:211], v[78:81]
	v_mfma_f32_16x16x32_bf16 v[74:77], v[158:161], v[208:211], v[74:77]
	s_setprio 0
	s_barrier
	s_add_i32 s37, s37, s53
	s_mov_b32 m0, s37
	ds_read_b128 v[162:165], v221 offset:49152
	ds_read_b128 v[166:169], v221 offset:50176
	ds_read_b128 v[170:173], v221 offset:51200
	ds_read_b128 v[174:177], v221 offset:52224
	ds_read_b128 v[196:199], v221 offset:53248
	ds_read_b128 v[200:203], v221 offset:54272
	ds_read_b128 v[204:207], v221 offset:55296
	ds_read_b128 v[208:211], v221 offset:56320
	s_add_u32 s98, s10, 0x80
	s_addc_u32 s99, s11, 0
	global_load_lds_dwordx4 v184, s[98:99]
	s_add_i32 m0, s37, 0x2000
	s_add_u32 s10, s10, 0x40080
	s_addc_u32 s11, s11, 0
	s_add_i32 s37, s39, s53
	global_load_lds_dwordx4 v188, s[98:99]
	s_mov_b32 m0, s37
	s_nop 0
	global_load_lds_dwordx4 v184, s[10:11]
	s_add_i32 m0, s37, 0x2000
	s_nop 0
	global_load_lds_dwordx4 v188, s[10:11]
	s_add_u32 s98, s44, 0xfffc0080
	s_addc_u32 s99, s45, -1
	s_mov_b32 m0, s60
	s_nop 0
	global_load_lds_dwordx4 v182, s[98:99]
	s_mov_b32 m0, s61
	s_nop 0
	global_load_lds_dwordx4 v186, s[98:99]
	s_waitcnt vmcnt(8)
	s_waitcnt lgkmcnt(0)
	s_barrier
	s_setprio 1
	s_waitcnt lgkmcnt(0)
	v_mfma_f32_16x16x32_bf16 v[62:65], v[66:69], v[162:165], v[62:65]
	v_mfma_f32_16x16x32_bf16 v[54:57], v[86:89], v[162:165], v[54:57]
	v_mfma_f32_16x16x32_bf16 v[46:49], v[66:69], v[170:173], v[46:49]
	v_mfma_f32_16x16x32_bf16 v[42:45], v[86:89], v[170:173], v[42:45]
	v_mfma_f32_16x16x32_bf16 v[30:33], v[66:69], v[196:199], v[30:33]
	v_mfma_f32_16x16x32_bf16 v[26:29], v[86:89], v[196:199], v[26:29]
	v_mfma_f32_16x16x32_bf16 v[14:17], v[66:69], v[204:207], v[14:17]
	v_mfma_f32_16x16x32_bf16 v[10:13], v[86:89], v[204:207], v[10:13]
	v_mfma_f32_16x16x32_bf16 v[62:65], v[70:73], v[166:169], v[62:65]
	v_mfma_f32_16x16x32_bf16 v[54:57], v[106:109], v[166:169], v[54:57]
	v_mfma_f32_16x16x32_bf16 v[46:49], v[70:73], v[174:177], v[46:49]
	v_mfma_f32_16x16x32_bf16 v[42:45], v[106:109], v[174:177], v[42:45]
	v_mfma_f32_16x16x32_bf16 v[30:33], v[70:73], v[200:203], v[30:33]
	v_mfma_f32_16x16x32_bf16 v[26:29], v[106:109], v[200:203], v[26:29]
	v_mfma_f32_16x16x32_bf16 v[14:17], v[70:73], v[208:211], v[14:17]
	v_mfma_f32_16x16x32_bf16 v[10:13], v[106:109], v[208:211], v[10:13]
	s_setprio 0
	s_setprio 1
	v_mfma_f32_16x16x32_bf16 v[58:61], v[146:149], v[162:165], v[58:61]
	v_mfma_f32_16x16x32_bf16 v[50:53], v[154:157], v[162:165], v[50:53]
	v_mfma_f32_16x16x32_bf16 v[38:41], v[146:149], v[170:173], v[38:41]
	v_mfma_f32_16x16x32_bf16 v[34:37], v[154:157], v[170:173], v[34:37]
	v_mfma_f32_16x16x32_bf16 v[22:25], v[146:149], v[196:199], v[22:25]
	v_mfma_f32_16x16x32_bf16 v[18:21], v[154:157], v[196:199], v[18:21]
	v_mfma_f32_16x16x32_bf16 v[6:9], v[146:149], v[204:207], v[6:9]
	v_mfma_f32_16x16x32_bf16 v[2:5], v[154:157], v[204:207], v[2:5]
	v_mfma_f32_16x16x32_bf16 v[58:61], v[150:153], v[166:169], v[58:61]
	v_mfma_f32_16x16x32_bf16 v[50:53], v[158:161], v[166:169], v[50:53]
	v_mfma_f32_16x16x32_bf16 v[38:41], v[150:153], v[174:177], v[38:41]
	v_mfma_f32_16x16x32_bf16 v[34:37], v[158:161], v[174:177], v[34:37]
	v_mfma_f32_16x16x32_bf16 v[22:25], v[150:153], v[200:203], v[22:25]
	v_mfma_f32_16x16x32_bf16 v[18:21], v[158:161], v[200:203], v[18:21]
	v_mfma_f32_16x16x32_bf16 v[6:9], v[150:153], v[208:211], v[6:9]
	v_mfma_f32_16x16x32_bf16 v[2:5], v[158:161], v[208:211], v[2:5]
	s_setprio 0
	s_barrier
	s_add_i32 s22, s22, 2
	s_add_u32 s8, s8, 0x100
	s_addc_u32 s9, s9, 0
	s_add_u32 s5, s5, 0x100
	s_addc_u32 s7, s7, 0
	s_cmp_gt_u32 s22, 13
	s_cbranch_scc1 .Lpeel_x4
.LBB0_991:
	ds_read_b128 v[66:69], v219
	ds_read_b128 v[70:73], v219 offset:1024
	ds_read_b128 v[86:89], v219 offset:2048
	ds_read_b128 v[106:109], v219 offset:3072
	ds_read_b128 v[146:149], v220
	ds_read_b128 v[150:153], v220 offset:1024
	ds_read_b128 v[154:157], v220 offset:2048
	ds_read_b128 v[158:161], v220 offset:3072
	s_add_u32 s10, s8, 0xfffc0080
	s_addc_u32 s11, s9, -1
	s_cmp_eq_u32 s22, 12
	s_cselect_b32 s45, s1, s11
	s_cselect_b32 s44, s2, s10
	s_cselect_b32 s11, s3, s7
	s_cselect_b32 s10, s4, s5
	s_add_i32 m0, s54, 0xc000
	ds_read_b128 v[162:165], v221
	ds_read_b128 v[166:169], v221 offset:1024
	ds_read_b128 v[170:173], v221 offset:2048
	ds_read_b128 v[174:177], v221 offset:3072
	ds_read_b128 v[196:199], v221 offset:4096
	ds_read_b128 v[200:203], v221 offset:5120
	ds_read_b128 v[204:207], v221 offset:6144
	ds_read_b128 v[208:211], v221 offset:7168
	global_load_lds_dwordx4 v192, s[8:9]
	s_add_i32 m0, s54, 0xe000
	s_nop 0
	global_load_lds_dwordx4 v194, s[8:9]
	s_waitcnt vmcnt(8)
	s_waitcnt lgkmcnt(0)
	s_barrier
	s_setprio 1
	s_waitcnt lgkmcnt(0)
	v_mfma_f32_16x16x32_bf16 v[142:145], v[66:69], v[162:165], v[142:145]
	v_mfma_f32_16x16x32_bf16 v[134:137], v[86:89], v[162:165], v[134:137]
	v_mfma_f32_16x16x32_bf16 v[126:129], v[66:69], v[170:173], v[126:129]
	v_mfma_f32_16x16x32_bf16 v[122:125], v[86:89], v[170:173], v[122:125]
	v_mfma_f32_16x16x32_bf16 v[110:113], v[66:69], v[196:199], v[110:113]
	v_mfma_f32_16x16x32_bf16 v[102:105], v[86:89], v[196:199], v[102:105]
	v_mfma_f32_16x16x32_bf16 v[90:93], v[66:69], v[204:207], v[90:93]
	v_mfma_f32_16x16x32_bf16 v[82:85], v[86:89], v[204:207], v[82:85]
	v_mfma_f32_16x16x32_bf16 v[142:145], v[70:73], v[166:169], v[142:145]
	v_mfma_f32_16x16x32_bf16 v[134:137], v[106:109], v[166:169], v[134:137]
	v_mfma_f32_16x16x32_bf16 v[126:129], v[70:73], v[174:177], v[126:129]
	v_mfma_f32_16x16x32_bf16 v[122:125], v[106:109], v[174:177], v[122:125]
	v_mfma_f32_16x16x32_bf16 v[110:113], v[70:73], v[200:203], v[110:113]
	v_mfma_f32_16x16x32_bf16 v[102:105], v[106:109], v[200:203], v[102:105]
	v_mfma_f32_16x16x32_bf16 v[90:93], v[70:73], v[208:211], v[90:93]
	v_mfma_f32_16x16x32_bf16 v[82:85], v[106:109], v[208:211], v[82:85]
	s_setprio 0
	s_setprio 1
	v_mfma_f32_16x16x32_bf16 v[138:141], v[146:149], v[162:165], v[138:141]
	v_mfma_f32_16x16x32_bf16 v[130:133], v[154:157], v[162:165], v[130:133]
	v_mfma_f32_16x16x32_bf16 v[118:121], v[146:149], v[170:173], v[118:121]
	v_mfma_f32_16x16x32_bf16 v[114:117], v[154:157], v[170:173], v[114:117]
	v_mfma_f32_16x16x32_bf16 v[98:101], v[146:149], v[196:199], v[98:101]
	v_mfma_f32_16x16x32_bf16 v[94:97], v[154:157], v[196:199], v[94:97]
	v_mfma_f32_16x16x32_bf16 v[78:81], v[146:149], v[204:207], v[78:81]
	v_mfma_f32_16x16x32_bf16 v[74:77], v[154:157], v[204:207], v[74:77]
	v_mfma_f32_16x16x32_bf16 v[138:141], v[150:153], v[166:169], v[138:141]
	v_mfma_f32_16x16x32_bf16 v[130:133], v[158:161], v[166:169], v[130:133]
	v_mfma_f32_16x16x32_bf16 v[118:121], v[150:153], v[174:177], v[118:121]
	v_mfma_f32_16x16x32_bf16 v[114:117], v[158:161], v[174:177], v[114:117]
	v_mfma_f32_16x16x32_bf16 v[98:101], v[150:153], v[200:203], v[98:101]
	v_mfma_f32_16x16x32_bf16 v[94:97], v[158:161], v[200:203], v[94:97]
	v_mfma_f32_16x16x32_bf16 v[78:81], v[150:153], v[208:211], v[78:81]
	v_mfma_f32_16x16x32_bf16 v[74:77], v[158:161], v[208:211], v[74:77]
	s_setprio 0
	s_barrier
	s_add_i32 s37, s62, s53
	s_mov_b32 m0, s37
	ds_read_b128 v[162:165], v221 offset:16384
	ds_read_b128 v[166:169], v221 offset:17408
	ds_read_b128 v[170:173], v221 offset:18432
	ds_read_b128 v[174:177], v221 offset:19456
	ds_read_b128 v[196:199], v221 offset:20480
	ds_read_b128 v[200:203], v221 offset:21504
	ds_read_b128 v[204:207], v221 offset:22528
	ds_read_b128 v[208:211], v221 offset:23552
	global_load_lds_dwordx4 v184, s[10:11]
	s_add_i32 m0, s37, 0x2000
	s_add_u32 s46, s10, 0x40000
	s_addc_u32 s47, s11, 0
	s_add_i32 s37, s63, s53
	global_load_lds_dwordx4 v188, s[10:11]
	s_mov_b32 m0, s37
	s_nop 0
	global_load_lds_dwordx4 v184, s[46:47]
	s_add_i32 m0, s37, 0x2000
	s_nop 0
	global_load_lds_dwordx4 v188, s[46:47]
	s_mov_b32 m0, s54
	s_nop 0
	global_load_lds_dwordx4 v182, s[44:45]
	s_mov_b32 m0, s55
	s_nop 0
	global_load_lds_dwordx4 v186, s[44:45]
	s_waitcnt vmcnt(8)
	s_waitcnt lgkmcnt(0)
	s_barrier
	s_setprio 1
	s_waitcnt lgkmcnt(0)
	v_mfma_f32_16x16x32_bf16 v[62:65], v[66:69], v[162:165], v[62:65]
	v_mfma_f32_16x16x32_bf16 v[54:57], v[86:89], v[162:165], v[54:57]
	v_mfma_f32_16x16x32_bf16 v[46:49], v[66:69], v[170:173], v[46:49]
	v_mfma_f32_16x16x32_bf16 v[42:45], v[86:89], v[170:173], v[42:45]
	v_mfma_f32_16x16x32_bf16 v[30:33], v[66:69], v[196:199], v[30:33]
	v_mfma_f32_16x16x32_bf16 v[26:29], v[86:89], v[196:199], v[26:29]
	v_mfma_f32_16x16x32_bf16 v[14:17], v[66:69], v[204:207], v[14:17]
	v_mfma_f32_16x16x32_bf16 v[10:13], v[86:89], v[204:207], v[10:13]
	v_mfma_f32_16x16x32_bf16 v[62:65], v[70:73], v[166:169], v[62:65]
	v_mfma_f32_16x16x32_bf16 v[54:57], v[106:109], v[166:169], v[54:57]
	v_mfma_f32_16x16x32_bf16 v[46:49], v[70:73], v[174:177], v[46:49]
	v_mfma_f32_16x16x32_bf16 v[42:45], v[106:109], v[174:177], v[42:45]
	v_mfma_f32_16x16x32_bf16 v[30:33], v[70:73], v[200:203], v[30:33]
	v_mfma_f32_16x16x32_bf16 v[26:29], v[106:109], v[200:203], v[26:29]
	v_mfma_f32_16x16x32_bf16 v[14:17], v[70:73], v[208:211], v[14:17]
	v_mfma_f32_16x16x32_bf16 v[10:13], v[106:109], v[208:211], v[10:13]
	s_setprio 0
	s_setprio 1
	v_mfma_f32_16x16x32_bf16 v[58:61], v[146:149], v[162:165], v[58:61]
	v_mfma_f32_16x16x32_bf16 v[50:53], v[154:157], v[162:165], v[50:53]
	v_mfma_f32_16x16x32_bf16 v[38:41], v[146:149], v[170:173], v[38:41]
	v_mfma_f32_16x16x32_bf16 v[34:37], v[154:157], v[170:173], v[34:37]
	v_mfma_f32_16x16x32_bf16 v[22:25], v[146:149], v[196:199], v[22:25]
	v_mfma_f32_16x16x32_bf16 v[18:21], v[154:157], v[196:199], v[18:21]
	v_mfma_f32_16x16x32_bf16 v[6:9], v[146:149], v[204:207], v[6:9]
	v_mfma_f32_16x16x32_bf16 v[2:5], v[154:157], v[204:207], v[2:5]
	v_mfma_f32_16x16x32_bf16 v[58:61], v[150:153], v[166:169], v[58:61]
	v_mfma_f32_16x16x32_bf16 v[50:53], v[158:161], v[166:169], v[50:53]
	v_mfma_f32_16x16x32_bf16 v[38:41], v[150:153], v[174:177], v[38:41]
	v_mfma_f32_16x16x32_bf16 v[34:37], v[158:161], v[174:177], v[34:37]
	v_mfma_f32_16x16x32_bf16 v[22:25], v[150:153], v[200:203], v[22:25]
	v_mfma_f32_16x16x32_bf16 v[18:21], v[158:161], v[200:203], v[18:21]
	v_mfma_f32_16x16x32_bf16 v[6:9], v[150:153], v[208:211], v[6:9]
	v_mfma_f32_16x16x32_bf16 v[2:5], v[158:161], v[208:211], v[2:5]
	s_setprio 0
	s_barrier
	s_add_i32 s37, 0, 0x18000
	s_add_i32 s39, 0, 0x1c000
	ds_read_b128 v[66:69], v254
	ds_read_b128 v[70:73], v254 offset:1024
	ds_read_b128 v[86:89], v254 offset:2048
	ds_read_b128 v[106:109], v254 offset:3072
	ds_read_b128 v[146:149], v255
	ds_read_b128 v[150:153], v255 offset:1024
	ds_read_b128 v[154:157], v255 offset:2048
	ds_read_b128 v[158:161], v255 offset:3072
	s_add_u32 s44, s44, 0x40000
	s_addc_u32 s45, s45, 0
	s_mov_b32 m0, s56
	ds_read_b128 v[162:165], v221 offset:32768
	ds_read_b128 v[166:169], v221 offset:33792
	ds_read_b128 v[170:173], v221 offset:34816
	ds_read_b128 v[174:177], v221 offset:35840
	ds_read_b128 v[196:199], v221 offset:36864
	ds_read_b128 v[200:203], v221 offset:37888
	ds_read_b128 v[204:207], v221 offset:38912
	ds_read_b128 v[208:211], v221 offset:39936
	global_load_lds_dwordx4 v182, s[44:45]
	s_mov_b32 m0, s57
	s_nop 0
	global_load_lds_dwordx4 v186, s[44:45]
	s_waitcnt vmcnt(8)
	s_waitcnt lgkmcnt(0)
	s_barrier
	s_setprio 1
	s_waitcnt lgkmcnt(0)
	v_mfma_f32_16x16x32_bf16 v[142:145], v[66:69], v[162:165], v[142:145]
	v_mfma_f32_16x16x32_bf16 v[134:137], v[86:89], v[162:165], v[134:137]
	v_mfma_f32_16x16x32_bf16 v[126:129], v[66:69], v[170:173], v[126:129]
	v_mfma_f32_16x16x32_bf16 v[122:125], v[86:89], v[170:173], v[122:125]
	v_mfma_f32_16x16x32_bf16 v[110:113], v[66:69], v[196:199], v[110:113]
	v_mfma_f32_16x16x32_bf16 v[102:105], v[86:89], v[196:199], v[102:105]
	v_mfma_f32_16x16x32_bf16 v[90:93], v[66:69], v[204:207], v[90:93]
	v_mfma_f32_16x16x32_bf16 v[82:85], v[86:89], v[204:207], v[82:85]
	v_mfma_f32_16x16x32_bf16 v[142:145], v[70:73], v[166:169], v[142:145]
	v_mfma_f32_16x16x32_bf16 v[134:137], v[106:109], v[166:169], v[134:137]
	v_mfma_f32_16x16x32_bf16 v[126:129], v[70:73], v[174:177], v[126:129]
	v_mfma_f32_16x16x32_bf16 v[122:125], v[106:109], v[174:177], v[122:125]
	v_mfma_f32_16x16x32_bf16 v[110:113], v[70:73], v[200:203], v[110:113]
	v_mfma_f32_16x16x32_bf16 v[102:105], v[106:109], v[200:203], v[102:105]
	v_mfma_f32_16x16x32_bf16 v[90:93], v[70:73], v[208:211], v[90:93]
	v_mfma_f32_16x16x32_bf16 v[82:85], v[106:109], v[208:211], v[82:85]
	s_setprio 0
	s_setprio 1
	v_mfma_f32_16x16x32_bf16 v[138:141], v[146:149], v[162:165], v[138:141]
	v_mfma_f32_16x16x32_bf16 v[130:133], v[154:157], v[162:165], v[130:133]
	v_mfma_f32_16x16x32_bf16 v[118:121], v[146:149], v[170:173], v[118:121]
	v_mfma_f32_16x16x32_bf16 v[114:117], v[154:157], v[170:173], v[114:117]
	v_mfma_f32_16x16x32_bf16 v[98:101], v[146:149], v[196:199], v[98:101]
	v_mfma_f32_16x16x32_bf16 v[94:97], v[154:157], v[196:199], v[94:97]
	v_mfma_f32_16x16x32_bf16 v[78:81], v[146:149], v[204:207], v[78:81]
	v_mfma_f32_16x16x32_bf16 v[74:77], v[154:157], v[204:207], v[74:77]
	v_mfma_f32_16x16x32_bf16 v[138:141], v[150:153], v[166:169], v[138:141]
	v_mfma_f32_16x16x32_bf16 v[130:133], v[158:161], v[166:169], v[130:133]
	v_mfma_f32_16x16x32_bf16 v[118:121], v[150:153], v[174:177], v[118:121]
	v_mfma_f32_16x16x32_bf16 v[114:117], v[158:161], v[174:177], v[114:117]
	v_mfma_f32_16x16x32_bf16 v[98:101], v[150:153], v[200:203], v[98:101]
	v_mfma_f32_16x16x32_bf16 v[94:97], v[158:161], v[200:203], v[94:97]
	v_mfma_f32_16x16x32_bf16 v[78:81], v[150:153], v[208:211], v[78:81]
	v_mfma_f32_16x16x32_bf16 v[74:77], v[158:161], v[208:211], v[74:77]
	s_setprio 0
	s_barrier
	s_add_i32 s37, s37, s53
	s_mov_b32 m0, s37
	ds_read_b128 v[162:165], v221 offset:49152
	ds_read_b128 v[166:169], v221 offset:50176
	ds_read_b128 v[170:173], v221 offset:51200
	ds_read_b128 v[174:177], v221 offset:52224
	ds_read_b128 v[196:199], v221 offset:53248
	ds_read_b128 v[200:203], v221 offset:54272
	ds_read_b128 v[204:207], v221 offset:55296
	ds_read_b128 v[208:211], v221 offset:56320
	s_add_u32 s98, s10, 0x80
	s_addc_u32 s99, s11, 0
	global_load_lds_dwordx4 v184, s[98:99]
	s_add_i32 m0, s37, 0x2000
	s_add_u32 s10, s10, 0x40080
	s_addc_u32 s11, s11, 0
	s_add_i32 s37, s39, s53
	global_load_lds_dwordx4 v188, s[98:99]
	s_mov_b32 m0, s37
	s_nop 0
	global_load_lds_dwordx4 v184, s[10:11]
	s_add_i32 m0, s37, 0x2000
	s_nop 0
	global_load_lds_dwordx4 v188, s[10:11]
	s_add_u32 s98, s44, 0xfffc0080
	s_addc_u32 s99, s45, -1
	s_mov_b32 m0, s60
	s_nop 0
	global_load_lds_dwordx4 v182, s[98:99]
	s_mov_b32 m0, s61
	s_nop 0
	global_load_lds_dwordx4 v186, s[98:99]
	s_waitcnt vmcnt(8)
	s_waitcnt lgkmcnt(0)
	s_barrier
	s_setprio 1
	s_waitcnt lgkmcnt(0)
	v_mfma_f32_16x16x32_bf16 v[62:65], v[66:69], v[162:165], v[62:65]
	v_mfma_f32_16x16x32_bf16 v[54:57], v[86:89], v[162:165], v[54:57]
	v_mfma_f32_16x16x32_bf16 v[46:49], v[66:69], v[170:173], v[46:49]
	v_mfma_f32_16x16x32_bf16 v[42:45], v[86:89], v[170:173], v[42:45]
	v_mfma_f32_16x16x32_bf16 v[30:33], v[66:69], v[196:199], v[30:33]
	v_mfma_f32_16x16x32_bf16 v[26:29], v[86:89], v[196:199], v[26:29]
	v_mfma_f32_16x16x32_bf16 v[14:17], v[66:69], v[204:207], v[14:17]
	v_mfma_f32_16x16x32_bf16 v[10:13], v[86:89], v[204:207], v[10:13]
	v_mfma_f32_16x16x32_bf16 v[62:65], v[70:73], v[166:169], v[62:65]
	v_mfma_f32_16x16x32_bf16 v[54:57], v[106:109], v[166:169], v[54:57]
	v_mfma_f32_16x16x32_bf16 v[46:49], v[70:73], v[174:177], v[46:49]
	v_mfma_f32_16x16x32_bf16 v[42:45], v[106:109], v[174:177], v[42:45]
	v_mfma_f32_16x16x32_bf16 v[30:33], v[70:73], v[200:203], v[30:33]
	v_mfma_f32_16x16x32_bf16 v[26:29], v[106:109], v[200:203], v[26:29]
	v_mfma_f32_16x16x32_bf16 v[14:17], v[70:73], v[208:211], v[14:17]
	v_mfma_f32_16x16x32_bf16 v[10:13], v[106:109], v[208:211], v[10:13]
	s_setprio 0
	s_setprio 1
	v_mfma_f32_16x16x32_bf16 v[58:61], v[146:149], v[162:165], v[58:61]
	v_mfma_f32_16x16x32_bf16 v[50:53], v[154:157], v[162:165], v[50:53]
	v_mfma_f32_16x16x32_bf16 v[38:41], v[146:149], v[170:173], v[38:41]
	v_mfma_f32_16x16x32_bf16 v[34:37], v[154:157], v[170:173], v[34:37]
	v_mfma_f32_16x16x32_bf16 v[22:25], v[146:149], v[196:199], v[22:25]
	v_mfma_f32_16x16x32_bf16 v[18:21], v[154:157], v[196:199], v[18:21]
	v_mfma_f32_16x16x32_bf16 v[6:9], v[146:149], v[204:207], v[6:9]
	v_mfma_f32_16x16x32_bf16 v[2:5], v[154:157], v[204:207], v[2:5]
	v_mfma_f32_16x16x32_bf16 v[58:61], v[150:153], v[166:169], v[58:61]
	v_mfma_f32_16x16x32_bf16 v[50:53], v[158:161], v[166:169], v[50:53]
	v_mfma_f32_16x16x32_bf16 v[38:41], v[150:153], v[174:177], v[38:41]
	v_mfma_f32_16x16x32_bf16 v[34:37], v[158:161], v[174:177], v[34:37]
	v_mfma_f32_16x16x32_bf16 v[22:25], v[150:153], v[200:203], v[22:25]
	v_mfma_f32_16x16x32_bf16 v[18:21], v[158:161], v[200:203], v[18:21]
	v_mfma_f32_16x16x32_bf16 v[6:9], v[150:153], v[208:211], v[6:9]
	v_mfma_f32_16x16x32_bf16 v[2:5], v[158:161], v[208:211], v[2:5]
	s_setprio 0
	s_barrier
	s_add_i32 s22, s22, 2
	s_add_u32 s8, s8, 0x100
	s_addc_u32 s9, s9, 0
	s_add_u32 s5, s5, 0x100
	s_addc_u32 s7, s7, 0
	s_cmp_gt_u32 s22, 13
	s_cbranch_scc0 .LBB0_991
